# stack + GEMM4 epilogue priority see-saw (alternating s_setprio along the epilogue so the two waves of a SIMD finish together)
# speedup vs baseline: 1.0129x; 1.0129x over previous
; __device__ __forceinline__ float fexp2(float x) { return __builtin_amdgcn_exp2f(x); }
;     __device__ __forceinline__ void operator()(f32x4 (&acc)[2][2][4][2], const Unit& u, int wr, int wc, int fr, int fq) const {
;     ...
; #pragma unroll
;         for (int ai = 0; ai < 2; ++ai)
; #pragma unroll
;             for (int m = 0; m < 4; ++m) { const float rs = row_rs(PS, row0 + ai * HALF + m * 16, fq);
; #pragma unroll
;                 for (int bj = 0; bj < 2; ++bj) { acc[ai][bj][m][0] *= rs; acc[ai][bj][m][1] *= rs; } }
;         if (fr < 2 || fr >= 14) {
; #pragma unroll
;             for (int ai = 0; ai < 2; ++ai)
; #pragma unroll
;                 for (int bj = 0; bj < 2; ++bj) { const f32x4 a0 = (fr < 2) ? acc[ai][bj][0][0] : acc[ai][bj][3][0], a1 = (fr < 2) ? acc[ai][bj][0][1] : acc[ai][bj][3][1];
;                     u32x4 w; w.x = cvt_pk_bf16(a0[0], a0[1]); w.y = cvt_pk_bf16(a0[2], a0[3]); w.z = cvt_pk_bf16(a1[0], a1[1]); w.w = cvt_pk_bf16(a1[2], a1[3]);
;                     *(u32x4*)(halo + ((size_t)((u.pm * 4 + ai * 2 + wr) * 4) + (fr < 2 ? fr : fr - 12)) * 5632 + bj * 2816 + f0) = w; } }
; #pragma unroll
;         for (int ai = 0; ai < 2; ++ai) {
;             unsigned pk[4][2][2];
; #pragma unroll
;             for (int n = 0; n < 2; ++n) {
;     ...
;                 const f32x4 wg0 = CQ4(0, 0), wg1 = CQ4(0, 1), wg2 = CQ4(0, 2), bg = CQ4(0, 3);
;                 const f32x4 wv0 = CQ4(1, 0), wv1 = CQ4(1, 1), wv2 = CQ4(1, 2), bv = CQ4(1, 3);
;     ...
;                 f32x4 pg1 = {0.f, 0.f, 0.f, 0.f}, pg2 = pg1, pv1 = pg1, pv2 = pg1;
; #pragma unroll
;                 for (int m = 0; m < 4; ++m) {
;                     const f32x4 zg = acc[ai][0][m][n], zv = acc[ai][1][m][n];
;                     f32x4 g1, g2, v1, v2;
; #pragma unroll
;                     for (int j = 0; j < 4; ++j) { g1[j] = dpp_shr1(pg1[j], zg[j]); g2[j] = dpp_shr2(pg2[j], zg[j]); v1[j] = dpp_shr1(pv1[j], zv[j]); v2[j] = dpp_shr2(pv2[j], zv[j]);
;                         pg1[j] = dpp_ror1(zg[j]); pg2[j] = dpp_ror2(zg[j]); pv1[j] = dpp_ror1(zv[j]); pv2[j] = dpp_ror2(zv[j]); }
;                     const f32x4 cg_ = bg + wg0 * g2 + wg1 * g1 + wg2 * zg, cv_ = bv + wv0 * v2 + wv1 * v1 + wv2 * zv;
;                     float o[4];
; #pragma unroll
;                     for (int j = 0; j < 4; ++j) o[j] = cg_[j] * frcp(1.0f + fexp2(-1.4426950409f * cg_[j])) * cv_[j];
.LBB0_40:
	s_or_b64 exec, exec, s[18:19]
	s_nop 0
	v_fmamk_f32 v144, v163, 0x3a800000, v196
	v_mul_f32_e32 v145, 0x4b800000, v144
	v_cmp_gt_f32_e32 vcc, s13, v144
	s_movk_i32 s22, 0x1600
	s_setprio 1
	v_or_b32_e32 v249, 16, v176
	v_cndmask_b32_e32 v144, v144, v145, vcc
	v_rsq_f32_e32 v144, v144
	v_or_b32_e32 v250, 32, v176
	v_or_b32_e32 v251, 48, v176
	v_add_u32_e32 v246, 0x80, v176
	v_mul_f32_e32 v145, 0x45800000, v144
	v_cndmask_b32_e32 v144, v144, v145, vcc
	v_pk_mul_f32 v[226:227], v[56:57], v[144:145] op_sel_hi:[1,0]
	v_fmamk_f32 v56, v162, 0x3a800000, v196
	v_mul_f32_e32 v57, 0x4b800000, v56
	v_cmp_gt_f32_e32 vcc, s13, v56
	v_pk_mul_f32 v[210:211], v[44:45], v[144:145] op_sel_hi:[1,0]
	v_pk_mul_f32 v[214:215], v[62:63], v[144:145] op_sel_hi:[1,0]
	v_cndmask_b32_e32 v56, v56, v57, vcc
	v_rsq_f32_e32 v56, v56
	v_lshlrev_b32_e32 v62, 16, v96
	v_and_b32_e32 v63, 0xffff0000, v96
	v_pk_mul_f32 v[230:231], v[66:67], v[144:145] op_sel_hi:[1,0]
	v_mul_f32_e32 v44, 0x45800000, v56
	v_cndmask_b32_e32 v44, v56, v44, vcc
	v_pk_mul_f32 v[202:203], v[36:37], v[44:45] op_sel_hi:[1,0]
	v_fmamk_f32 v36, v123, 0x3a800000, v196
	v_mul_f32_e32 v37, 0x4b800000, v36
	v_cmp_gt_f32_e32 vcc, s13, v36
	v_pk_mul_f32 v[206:207], v[50:51], v[44:45] op_sel_hi:[1,0]
	v_lshlrev_b32_e32 v50, 16, v84
	v_cndmask_b32_e32 v36, v36, v37, vcc
	v_rsq_f32_e32 v36, v36
	v_and_b32_e32 v51, 0xffff0000, v84
	v_pk_mul_f32 v[222:223], v[54:55], v[44:45] op_sel_hi:[1,0]
	v_pk_mul_f32 v[208:209], v[48:49], v[44:45] op_sel_hi:[1,0]
	v_mul_f32_e32 v37, 0x45800000, v36
	v_cndmask_b32_e32 v36, v36, v37, vcc
	v_pk_mul_f32 v[162:163], v[24:25], v[36:37] op_sel_hi:[1,0]
	v_fmamk_f32 v24, v122, 0x3a800000, v196
	v_mul_f32_e32 v25, 0x4b800000, v24
	v_cmp_gt_f32_e32 vcc, s13, v24
	v_pk_mul_f32 v[180:181], v[34:35], v[36:37] op_sel_hi:[1,0]
	v_pk_mul_f32 v[34:35], v[28:29], v[36:37] op_sel_hi:[1,0]
	v_cndmask_b32_e32 v24, v24, v25, vcc
	v_rsq_f32_e32 v24, v24
	v_pk_mul_f32 v[28:29], v[12:13], v[36:37] op_sel_hi:[1,0]
	v_lshlrev_b32_e32 v54, 16, v88
	v_and_b32_e32 v55, 0xffff0000, v88
	v_mul_f32_e32 v12, 0x45800000, v24
	v_cndmask_b32_e32 v12, v24, v12, vcc
	v_pk_mul_f32 v[146:147], v[22:23], v[12:13] op_sel_hi:[1,0]
	v_pk_mul_f32 v[22:23], v[6:7], v[12:13] op_sel_hi:[1,0]
	v_mov_b32_e32 v6, v2
	v_mov_b32_e32 v7, v2
	v_pk_mul_f32 v[148:149], v[20:21], v[12:13] op_sel_hi:[1,0]
	v_pk_mul_f32 v[20:21], v[4:5], v[12:13] op_sel_hi:[1,0]
	v_mov_b32_e32 v4, v2
	v_mov_b32_dpp v6, v192 row_shr:2 row_mask:0xf bank_mask:0xf
	v_mov_b32_e32 v5, v2
	v_mov_b32_dpp v7, v193 row_shr:2 row_mask:0xf bank_mask:0xf
	v_lshlrev_b32_e32 v48, 16, v89
	v_and_b32_e32 v49, 0xffff0000, v89
	v_mov_b32_dpp v4, v192 row_shr:1 row_mask:0xf bank_mask:0xf
	v_mov_b32_dpp v5, v193 row_shr:1 row_mask:0xf bank_mask:0xf
	v_mov_b32_e32 v88, v2
	v_mov_b32_e32 v89, v2
	v_pk_fma_f32 v[6:7], v[50:51], v[6:7], v[62:63]
	v_pk_mul_f32 v[228:229], v[58:59], v[144:145] op_sel_hi:[1,0]
	v_pk_mul_f32 v[224:225], v[52:53], v[44:45] op_sel_hi:[1,0]
	v_pk_mul_f32 v[220:221], v[42:43], v[44:45] op_sel_hi:[1,0]
	v_pk_mul_f32 v[218:219], v[40:41], v[44:45] op_sel_hi:[1,0]
	v_pk_mul_f32 v[204:205], v[38:39], v[44:45] op_sel_hi:[1,0]
	v_lshlrev_b32_e32 v58, 16, v85
	v_and_b32_e32 v59, 0xffff0000, v85
	v_lshlrev_b32_e32 v44, 16, v92
	v_and_b32_e32 v45, 0xffff0000, v92
	v_lshlrev_b32_e32 v66, 16, v97
	v_and_b32_e32 v67, 0xffff0000, v97
	v_mov_b32_e32 v84, v2
	v_mov_b32_dpp v88, v194 row_shr:2 row_mask:0xf bank_mask:0xf
	v_mov_b32_e32 v85, v2
	v_mov_b32_dpp v89, v195 row_shr:2 row_mask:0xf bank_mask:0xf
	v_pk_fma_f32 v[4:5], v[54:55], v[4:5], v[6:7]
	v_mov_b32_dpp v84, v194 row_shr:1 row_mask:0xf bank_mask:0xf
	v_mov_b32_dpp v85, v195 row_shr:1 row_mask:0xf bank_mask:0xf
	v_pk_fma_f32 v[88:89], v[58:59], v[88:89], v[66:67]
	v_pk_fma_f32 v[4:5], v[192:193], v[44:45], v[4:5]
	v_pk_fma_f32 v[6:7], v[48:49], v[84:85], v[88:89]
	v_mul_f32_e32 v88, 0xbfb8aa3b, v4
	v_exp_f32_e32 v88, v88
	v_pk_mul_f32 v[232:233], v[64:65], v[144:145] op_sel_hi:[1,0]
	v_pk_mul_f32 v[216:217], v[60:61], v[144:145] op_sel_hi:[1,0]
	v_pk_mul_f32 v[212:213], v[46:47], v[144:145] op_sel_hi:[1,0]
	v_pk_mul_f32 v[144:145], v[10:11], v[12:13] op_sel_hi:[1,0]
	v_mov_b32_e32 v10, v2
	v_mov_b32_e32 v11, v2
	v_mov_b32_e32 v96, v2
	v_mov_b32_e32 v97, v2
	v_pk_mul_f32 v[122:123], v[8:9], v[12:13] op_sel_hi:[1,0]
	v_lshlrev_b32_e32 v52, 16, v93
	v_and_b32_e32 v53, 0xffff0000, v93
	v_lshlrev_b32_e32 v46, 16, v100
	v_and_b32_e32 v47, 0xffff0000, v100
	v_lshlrev_b32_e32 v56, 16, v101
	v_and_b32_e32 v57, 0xffff0000, v101
	v_lshlrev_b32_e32 v60, 16, v112
	v_and_b32_e32 v61, 0xffff0000, v112
	v_lshlrev_b32_e32 v64, 16, v113
	v_and_b32_e32 v65, 0xffff0000, v113
	v_mov_b32_e32 v8, v2
	v_mov_b32_dpp v10, v188 row_shr:2 row_mask:0xf bank_mask:0xf
	v_mov_b32_e32 v9, v2
	v_mov_b32_dpp v11, v189 row_shr:2 row_mask:0xf bank_mask:0xf
	v_mov_b32_e32 v92, v2
	v_mov_b32_dpp v96, v190 row_shr:2 row_mask:0xf bank_mask:0xf
	v_mov_b32_e32 v93, v2
	v_mov_b32_dpp v97, v191 row_shr:2 row_mask:0xf bank_mask:0xf
	v_lshlrev_b32_e32 v38, 16, v104
	v_and_b32_e32 v39, 0xffff0000, v104
	v_lshlrev_b32_e32 v40, 16, v105
	v_and_b32_e32 v41, 0xffff0000, v105
	v_mov_b32_dpp v8, v188 row_shr:1 row_mask:0xf bank_mask:0xf
	v_mov_b32_dpp v9, v189 row_shr:1 row_mask:0xf bank_mask:0xf
	v_mov_b32_dpp v92, v190 row_shr:1 row_mask:0xf bank_mask:0xf
	v_mov_b32_dpp v93, v191 row_shr:1 row_mask:0xf bank_mask:0xf
	v_pk_fma_f32 v[84:85], v[56:57], v[96:97], v[64:65]
	v_pk_fma_f32 v[10:11], v[46:47], v[10:11], v[60:61]
	v_pk_mul_f32 v[182:183], v[32:33], v[36:37] op_sel_hi:[1,0]
	v_pk_fma_f32 v[8:9], v[38:39], v[8:9], v[10:11]
; __device__ __forceinline__ unsigned cvt_pk_bf16(float lo, float hi) { unsigned r; asm volatile("v_cvt_pk_bf16_f32 %0, %1, %2" : "=v"(r) : "v"(lo), "v"(hi)); return r; }
; __device__ __forceinline__ float fexp2(float x) { return __builtin_amdgcn_exp2f(x); }
; __device__ __forceinline__ float frcp(float x) { return __builtin_amdgcn_rcpf(x); }
; __device__ __forceinline__ float dpp_shr1(float old, float src) { return __int_as_float(__builtin_amdgcn_update_dpp(__float_as_int(old), __float_as_int(src), 0x111, 0xf, 0xf, false)); }
; __device__ __forceinline__ float dpp_shr2(float old, float src) { return __int_as_float(__builtin_amdgcn_update_dpp(__float_as_int(old), __float_as_int(src), 0x112, 0xf, 0xf, false)); }
; __device__ __forceinline__ float dpp_ror1(float src) { return __int_as_float(__builtin_amdgcn_mov_dpp(__float_as_int(src), 0x121, 0xf, 0xf, true)); }
; __device__ __forceinline__ float dpp_ror2(float src) { return __int_as_float(__builtin_amdgcn_mov_dpp(__float_as_int(src), 0x122, 0xf, 0xf, true)); }
;     __device__ __forceinline__ void operator()(f32x4 (&acc)[2][2][4][2], const Unit& u, int wr, int wc, int fr, int fq) const {
;     ...
;                 for (int m = 0; m < 4; ++m) {
;                     const f32x4 zg = acc[ai][0][m][n], zv = acc[ai][1][m][n];
;                     f32x4 g1, g2, v1, v2;
; #pragma unroll
;                     for (int j = 0; j < 4; ++j) { g1[j] = dpp_shr1(pg1[j], zg[j]); g2[j] = dpp_shr2(pg2[j], zg[j]); v1[j] = dpp_shr1(pv1[j], zv[j]); v2[j] = dpp_shr2(pv2[j], zv[j]);
;                         pg1[j] = dpp_ror1(zg[j]); pg2[j] = dpp_ror2(zg[j]); pv1[j] = dpp_ror1(zv[j]); pv2[j] = dpp_ror2(zv[j]); }
;                     const f32x4 cg_ = bg + wg0 * g2 + wg1 * g1 + wg2 * zg, cv_ = bv + wv0 * v2 + wv1 * v1 + wv2 * zv;
;                     float o[4];
; #pragma unroll
;                     for (int j = 0; j < 4; ++j) o[j] = cg_[j] * frcp(1.0f + fexp2(-1.4426950409f * cg_[j])) * cv_[j];
;                     pk[m][n][0] = cvt_pk_bf16(o[0], o[1]); pk[m][n][1] = cvt_pk_bf16(o[2], o[3]);
	v_pk_fma_f32 v[10:11], v[40:41], v[92:93], v[84:85]
	v_add_f32_e32 v84, 1.0, v88
	v_rcp_f32_e32 v84, v84
	v_mul_f32_e32 v85, 0xbfb8aa3b, v5
	v_exp_f32_e32 v85, v85
	v_pk_mul_f32 v[32:33], v[30:31], v[36:37] op_sel_hi:[1,0]
	v_pk_mul_f32 v[178:179], v[26:27], v[36:37] op_sel_hi:[1,0]
	v_pk_mul_f32 v[30:31], v[14:15], v[36:37] op_sel_hi:[1,0]
	v_lshlrev_b32_e32 v36, 16, v108
	v_and_b32_e32 v37, 0xffff0000, v108
	v_pk_fma_f32 v[6:7], v[194:195], v[52:53], v[6:7]
	v_pk_fma_f32 v[8:9], v[188:189], v[36:37], v[8:9]
	v_mul_f32_e32 v4, v4, v84
	v_mul_f32_e32 v4, v8, v4
	v_add_f32_e32 v8, 1.0, v85
	v_mul_f32_e32 v84, 0xbfb8aa3b, v6
	v_rcp_f32_e32 v8, v8
	v_exp_f32_e32 v84, v84
	v_mov_b32_dpp v14, v192 row_ror:2 row_mask:0xf bank_mask:0xf bound_ctrl:1
	v_mov_b32_dpp v15, v193 row_ror:2 row_mask:0xf bank_mask:0xf bound_ctrl:1
	v_mul_f32_e32 v5, v5, v8
	v_add_f32_e32 v8, 1.0, v84
	v_rcp_f32_e32 v8, v8
	v_pk_mul_f32 v[24:25], v[18:19], v[12:13] op_sel_hi:[1,0]
	v_pk_mul_f32 v[26:27], v[16:17], v[12:13] op_sel_hi:[1,0]
	v_mov_b32_dpp v12, v192 row_ror:1 row_mask:0xf bank_mask:0xf bound_ctrl:1
	v_mov_b32_dpp v13, v193 row_ror:1 row_mask:0xf bank_mask:0xf bound_ctrl:1
	v_mov_b32_dpp v14, v232 row_shr:2 row_mask:0xf bank_mask:0xf
	v_mov_b32_dpp v15, v233 row_shr:2 row_mask:0xf bank_mask:0xf
	v_mov_b32_dpp v104, v194 row_ror:2 row_mask:0xf bank_mask:0xf bound_ctrl:1
	v_mov_b32_dpp v105, v195 row_ror:2 row_mask:0xf bank_mask:0xf bound_ctrl:1
	v_mov_b32_dpp v12, v232 row_shr:1 row_mask:0xf bank_mask:0xf
	v_mov_b32_dpp v13, v233 row_shr:1 row_mask:0xf bank_mask:0xf
	v_pk_fma_f32 v[14:15], v[50:51], v[14:15], v[62:63]
	v_mov_b32_dpp v100, v194 row_ror:1 row_mask:0xf bank_mask:0xf bound_ctrl:1
	v_mov_b32_dpp v101, v195 row_ror:1 row_mask:0xf bank_mask:0xf bound_ctrl:1
	v_mov_b32_dpp v104, v230 row_shr:2 row_mask:0xf bank_mask:0xf
	v_mov_b32_dpp v105, v231 row_shr:2 row_mask:0xf bank_mask:0xf
	v_pk_fma_f32 v[12:13], v[54:55], v[12:13], v[14:15]
	v_mul_f32_e32 v5, v9, v5
	v_mul_f32_e32 v6, v6, v8
	v_mov_b32_dpp v100, v230 row_shr:1 row_mask:0xf bank_mask:0xf
	v_mov_b32_dpp v101, v231 row_shr:1 row_mask:0xf bank_mask:0xf
	v_pk_fma_f32 v[8:9], v[58:59], v[104:105], v[66:67]
	s_setprio 0
	v_pk_fma_f32 v[12:13], v[232:233], v[44:45], v[12:13]
	v_pk_fma_f32 v[8:9], v[48:49], v[100:101], v[8:9]
	v_mul_f32_e32 v100, 0xbfb8aa3b, v12
	v_exp_f32_e32 v100, v100
	v_mov_b32_dpp v18, v188 row_ror:2 row_mask:0xf bank_mask:0xf bound_ctrl:1
	v_mov_b32_dpp v19, v189 row_ror:2 row_mask:0xf bank_mask:0xf bound_ctrl:1
	v_mov_b32_dpp v16, v188 row_ror:1 row_mask:0xf bank_mask:0xf bound_ctrl:1
	v_mov_b32_dpp v17, v189 row_ror:1 row_mask:0xf bank_mask:0xf bound_ctrl:1
	v_mov_b32_dpp v18, v226 row_shr:2 row_mask:0xf bank_mask:0xf
	v_mov_b32_dpp v19, v227 row_shr:2 row_mask:0xf bank_mask:0xf
	v_mov_b32_dpp v16, v226 row_shr:1 row_mask:0xf bank_mask:0xf
	v_mov_b32_dpp v17, v227 row_shr:1 row_mask:0xf bank_mask:0xf
	v_pk_fma_f32 v[18:19], v[46:47], v[18:19], v[60:61]
	v_mul_f32_e32 v85, 0xbfb8aa3b, v7
	v_pk_fma_f32 v[16:17], v[38:39], v[16:17], v[18:19]
	v_add_f32_e32 v18, 1.0, v100
	v_rcp_f32_e32 v18, v18
	v_mul_f32_e32 v19, 0xbfb8aa3b, v13
	v_exp_f32_e32 v19, v19
	v_exp_f32_e32 v85, v85
	v_pk_fma_f32 v[8:9], v[230:231], v[52:53], v[8:9]
	v_pk_fma_f32 v[16:17], v[226:227], v[36:37], v[16:17]
	v_mul_f32_e32 v12, v12, v18
	v_mul_f32_e32 v12, v16, v12
	v_add_f32_e32 v16, 1.0, v19
	v_mul_f32_e32 v18, 0xbfb8aa3b, v8
	v_rcp_f32_e32 v16, v16
	v_exp_f32_e32 v18, v18
	v_mul_f32_e32 v19, 0xbfb8aa3b, v9
	v_add_f32_e32 v84, 1.0, v85
	v_exp_f32_e32 v19, v19
	v_rcp_f32_e32 v84, v84
	v_mul_f32_e32 v13, v13, v16
	v_add_f32_e32 v16, 1.0, v18
	v_lshlrev_b32_e32 v42, 16, v109
	v_and_b32_e32 v43, 0xffff0000, v109
	v_mov_b32_dpp v112, v190 row_ror:2 row_mask:0xf bank_mask:0xf bound_ctrl:1
	v_mov_b32_dpp v113, v191 row_ror:2 row_mask:0xf bank_mask:0xf bound_ctrl:1
	v_rcp_f32_e32 v16, v16
	v_add_f32_e32 v18, 1.0, v19
	v_mov_b32_dpp v108, v190 row_ror:1 row_mask:0xf bank_mask:0xf bound_ctrl:1
	v_mov_b32_dpp v109, v191 row_ror:1 row_mask:0xf bank_mask:0xf bound_ctrl:1
	v_pk_fma_f32 v[10:11], v[190:191], v[42:43], v[10:11]
	v_mul_f32_e32 v7, v7, v84
	v_mov_b32_dpp v112, v228 row_shr:2 row_mask:0xf bank_mask:0xf
	v_mov_b32_dpp v113, v229 row_shr:2 row_mask:0xf bank_mask:0xf
	v_rcp_f32_e32 v18, v18
	v_mul_f32_e32 v6, v10, v6
	v_mul_f32_e32 v7, v11, v7
	v_mov_b32_dpp v10, v232 row_ror:2 row_mask:0xf bank_mask:0xf bound_ctrl:1
	v_mov_b32_dpp v11, v233 row_ror:2 row_mask:0xf bank_mask:0xf bound_ctrl:1
	v_mov_b32_dpp v108, v228 row_shr:1 row_mask:0xf bank_mask:0xf
	v_mov_b32_dpp v109, v229 row_shr:1 row_mask:0xf bank_mask:0xf
	v_pk_fma_f32 v[14:15], v[56:57], v[112:113], v[64:65]
	v_cvt_pk_bf16_f32 v4, v4, v5
	v_cvt_pk_bf16_f32 v5, v6, v7
	v_mov_b32_dpp v6, v232 row_ror:1 row_mask:0xf bank_mask:0xf bound_ctrl:1
	v_mov_b32_dpp v7, v233 row_ror:1 row_mask:0xf bank_mask:0xf bound_ctrl:1
	v_pk_fma_f32 v[14:15], v[40:41], v[108:109], v[14:15]
	v_mov_b32_dpp v10, v224 row_shr:2 row_mask:0xf bank_mask:0xf
	v_mov_b32_dpp v11, v225 row_shr:2 row_mask:0xf bank_mask:0xf
	v_mov_b32_dpp v96, v230 row_ror:2 row_mask:0xf bank_mask:0xf bound_ctrl:1
	v_mov_b32_dpp v97, v231 row_ror:2 row_mask:0xf bank_mask:0xf bound_ctrl:1
	v_pk_fma_f32 v[14:15], v[228:229], v[42:43], v[14:15]
	v_mul_f32_e32 v8, v8, v16
	v_mov_b32_dpp v6, v224 row_shr:1 row_mask:0xf bank_mask:0xf
	v_mov_b32_dpp v7, v225 row_shr:1 row_mask:0xf bank_mask:0xf
	v_pk_fma_f32 v[10:11], v[50:51], v[10:11], v[62:63]
	v_mov_b32_dpp v92, v230 row_ror:1 row_mask:0xf bank_mask:0xf bound_ctrl:1
	v_mov_b32_dpp v93, v231 row_ror:1 row_mask:0xf bank_mask:0xf bound_ctrl:1
; __device__ __forceinline__ unsigned cvt_pk_bf16(float lo, float hi) { unsigned r; asm volatile("v_cvt_pk_bf16_f32 %0, %1, %2" : "=v"(r) : "v"(lo), "v"(hi)); return r; }
; __device__ __forceinline__ float fexp2(float x) { return __builtin_amdgcn_exp2f(x); }
; __device__ __forceinline__ float frcp(float x) { return __builtin_amdgcn_rcpf(x); }
; __device__ __forceinline__ float dpp_shr1(float old, float src) { return __int_as_float(__builtin_amdgcn_update_dpp(__float_as_int(old), __float_as_int(src), 0x111, 0xf, 0xf, false)); }
; __device__ __forceinline__ float dpp_shr2(float old, float src) { return __int_as_float(__builtin_amdgcn_update_dpp(__float_as_int(old), __float_as_int(src), 0x112, 0xf, 0xf, false)); }
; __device__ __forceinline__ float dpp_ror1(float src) { return __int_as_float(__builtin_amdgcn_mov_dpp(__float_as_int(src), 0x121, 0xf, 0xf, true)); }
; __device__ __forceinline__ float dpp_ror2(float src) { return __int_as_float(__builtin_amdgcn_mov_dpp(__float_as_int(src), 0x122, 0xf, 0xf, true)); }
;     __device__ __forceinline__ void operator()(f32x4 (&acc)[2][2][4][2], const Unit& u, int wr, int wc, int fr, int fq) const {
;     ...
;                 for (int m = 0; m < 4; ++m) {
;                     const f32x4 zg = acc[ai][0][m][n], zv = acc[ai][1][m][n];
;                     f32x4 g1, g2, v1, v2;
; #pragma unroll
;                     for (int j = 0; j < 4; ++j) { g1[j] = dpp_shr1(pg1[j], zg[j]); g2[j] = dpp_shr2(pg2[j], zg[j]); v1[j] = dpp_shr1(pv1[j], zv[j]); v2[j] = dpp_shr2(pv2[j], zv[j]);
;                         pg1[j] = dpp_ror1(zg[j]); pg2[j] = dpp_ror2(zg[j]); pv1[j] = dpp_ror1(zv[j]); pv2[j] = dpp_ror2(zv[j]); }
;                     const f32x4 cg_ = bg + wg0 * g2 + wg1 * g1 + wg2 * zg, cv_ = bv + wv0 * v2 + wv1 * v1 + wv2 * zv;
;                     float o[4];
; #pragma unroll
;                     for (int j = 0; j < 4; ++j) o[j] = cg_[j] * frcp(1.0f + fexp2(-1.4426950409f * cg_[j])) * cv_[j];
;                     pk[m][n][0] = cvt_pk_bf16(o[0], o[1]); pk[m][n][1] = cvt_pk_bf16(o[2], o[3]);
	v_mul_f32_e32 v13, v17, v13
	v_mul_f32_e32 v14, v14, v8
	v_mul_f32_e32 v8, v9, v18
	v_mov_b32_dpp v96, v222 row_shr:2 row_mask:0xf bank_mask:0xf
	v_mov_b32_dpp v97, v223 row_shr:2 row_mask:0xf bank_mask:0xf
	v_pk_fma_f32 v[6:7], v[54:55], v[6:7], v[10:11]
	v_mul_f32_e32 v9, v15, v8
	v_cvt_pk_bf16_f32 v8, v12, v13
	v_mov_b32_dpp v92, v222 row_shr:1 row_mask:0xf bank_mask:0xf
	v_mov_b32_dpp v93, v223 row_shr:1 row_mask:0xf bank_mask:0xf
	v_pk_fma_f32 v[12:13], v[58:59], v[96:97], v[66:67]
	v_pk_fma_f32 v[6:7], v[224:225], v[44:45], v[6:7]
	v_pk_fma_f32 v[10:11], v[48:49], v[92:93], v[12:13]
	v_mul_f32_e32 v92, 0xbfb8aa3b, v6
	v_exp_f32_e32 v92, v92
	v_mov_b32_dpp v88, v226 row_ror:2 row_mask:0xf bank_mask:0xf bound_ctrl:1
	v_mov_b32_dpp v89, v227 row_ror:2 row_mask:0xf bank_mask:0xf bound_ctrl:1
	v_mov_b32_dpp v84, v226 row_ror:1 row_mask:0xf bank_mask:0xf bound_ctrl:1
	v_mov_b32_dpp v85, v227 row_ror:1 row_mask:0xf bank_mask:0xf bound_ctrl:1
	v_mov_b32_dpp v88, v218 row_shr:2 row_mask:0xf bank_mask:0xf
	v_mov_b32_dpp v89, v219 row_shr:2 row_mask:0xf bank_mask:0xf
	v_mov_b32_dpp v84, v218 row_shr:1 row_mask:0xf bank_mask:0xf
	v_mov_b32_dpp v85, v219 row_shr:1 row_mask:0xf bank_mask:0xf
	v_pk_fma_f32 v[88:89], v[46:47], v[88:89], v[60:61]
	v_pk_fma_f32 v[10:11], v[222:223], v[52:53], v[10:11]
	v_pk_fma_f32 v[84:85], v[38:39], v[84:85], v[88:89]
	v_add_f32_e32 v88, 1.0, v92
	v_rcp_f32_e32 v88, v88
	v_mul_f32_e32 v89, 0xbfb8aa3b, v7
	v_exp_f32_e32 v89, v89
	v_pk_fma_f32 v[84:85], v[218:219], v[36:37], v[84:85]
	v_mul_f32_e32 v6, v6, v88
	v_mul_f32_e32 v6, v84, v6
	v_add_f32_e32 v84, 1.0, v89
	v_mul_f32_e32 v88, 0xbfb8aa3b, v10
	v_mul_f32_e32 v89, 0xbfb8aa3b, v11
	v_rcp_f32_e32 v84, v84
	v_exp_f32_e32 v88, v88
	v_exp_f32_e32 v89, v89
	v_mov_b32_dpp v190, v228 row_ror:2 row_mask:0xf bank_mask:0xf bound_ctrl:1
	v_mul_f32_e32 v7, v7, v84
	v_add_f32_e32 v84, 1.0, v88
	v_add_f32_e32 v88, 1.0, v89
	v_mov_b32_dpp v191, v229 row_ror:2 row_mask:0xf bank_mask:0xf bound_ctrl:1
	v_rcp_f32_e32 v84, v84
	v_rcp_f32_e32 v88, v88
	v_mov_b32_dpp v188, v228 row_ror:1 row_mask:0xf bank_mask:0xf bound_ctrl:1
	v_mov_b32_dpp v189, v229 row_ror:1 row_mask:0xf bank_mask:0xf bound_ctrl:1
	v_mov_b32_dpp v190, v220 row_shr:2 row_mask:0xf bank_mask:0xf
	v_mov_b32_dpp v191, v221 row_shr:2 row_mask:0xf bank_mask:0xf
	v_mov_b32_dpp v188, v220 row_shr:1 row_mask:0xf bank_mask:0xf
	v_mov_b32_dpp v189, v221 row_shr:1 row_mask:0xf bank_mask:0xf
	v_pk_fma_f32 v[12:13], v[56:57], v[190:191], v[64:65]
	v_mov_b32_dpp v16, v224 row_ror:2 row_mask:0xf bank_mask:0xf bound_ctrl:1
	v_pk_fma_f32 v[12:13], v[40:41], v[188:189], v[12:13]
	v_mov_b32_dpp v17, v225 row_ror:2 row_mask:0xf bank_mask:0xf bound_ctrl:1
	v_pk_fma_f32 v[12:13], v[220:221], v[42:43], v[12:13]
	v_mul_f32_e32 v10, v10, v84
	v_mul_f32_e32 v11, v11, v88
	v_cvt_pk_bf16_f32 v9, v14, v9
	v_mov_b32_dpp v14, v224 row_ror:1 row_mask:0xf bank_mask:0xf bound_ctrl:1
	v_mov_b32_dpp v15, v225 row_ror:1 row_mask:0xf bank_mask:0xf bound_ctrl:1
	v_mul_f32_e32 v10, v12, v10
	v_mul_f32_e32 v11, v13, v11
	v_mov_b32_dpp v16, v186 row_shr:2 row_mask:0xf bank_mask:0xf
	v_mov_b32_dpp v17, v187 row_shr:2 row_mask:0xf bank_mask:0xf
	v_mul_f32_e32 v7, v85, v7
	v_cvt_pk_bf16_f32 v12, v6, v7
	v_cvt_pk_bf16_f32 v13, v10, v11
	v_mov_b32_dpp v14, v186 row_shr:1 row_mask:0xf bank_mask:0xf
	v_mov_b32_dpp v15, v187 row_shr:1 row_mask:0xf bank_mask:0xf
	v_pk_fma_f32 v[10:11], v[50:51], v[16:17], v[62:63]
	v_mov_b32_dpp v100, v218 row_ror:2 row_mask:0xf bank_mask:0xf bound_ctrl:1
	v_pk_fma_f32 v[10:11], v[54:55], v[14:15], v[10:11]
	v_mov_b32_dpp v101, v219 row_ror:2 row_mask:0xf bank_mask:0xf bound_ctrl:1
	v_pk_fma_f32 v[10:11], v[186:187], v[44:45], v[10:11]
	v_mov_b32_dpp v18, v218 row_ror:1 row_mask:0xf bank_mask:0xf bound_ctrl:1
	v_mul_f32_e32 v84, 0xbfb8aa3b, v10
	v_exp_f32_e32 v84, v84
	v_mov_b32_dpp v19, v219 row_ror:1 row_mask:0xf bank_mask:0xf bound_ctrl:1
	v_mov_b32_dpp v100, v150 row_shr:2 row_mask:0xf bank_mask:0xf
	v_mov_b32_dpp v101, v151 row_shr:2 row_mask:0xf bank_mask:0xf
	v_mov_b32_dpp v18, v150 row_shr:1 row_mask:0xf bank_mask:0xf
	v_mov_b32_dpp v19, v151 row_shr:1 row_mask:0xf bank_mask:0xf
	v_pk_fma_f32 v[16:17], v[46:47], v[100:101], v[60:61]
	v_mov_b32_dpp v108, v222 row_ror:2 row_mask:0xf bank_mask:0xf bound_ctrl:1
	v_pk_fma_f32 v[16:17], v[38:39], v[18:19], v[16:17]
	v_add_f32_e32 v18, 1.0, v84
	s_setprio 1
	v_mov_b32_dpp v109, v223 row_ror:2 row_mask:0xf bank_mask:0xf bound_ctrl:1
	v_rcp_f32_e32 v18, v18
	v_mul_f32_e32 v19, 0xbfb8aa3b, v11
	v_mov_b32_dpp v104, v222 row_ror:1 row_mask:0xf bank_mask:0xf bound_ctrl:1
	v_mov_b32_dpp v105, v223 row_ror:1 row_mask:0xf bank_mask:0xf bound_ctrl:1
	v_mov_b32_dpp v108, v184 row_shr:2 row_mask:0xf bank_mask:0xf
	v_mov_b32_dpp v109, v185 row_shr:2 row_mask:0xf bank_mask:0xf
	v_exp_f32_e32 v19, v19
	v_mov_b32_dpp v104, v184 row_shr:1 row_mask:0xf bank_mask:0xf
	v_mov_b32_dpp v105, v185 row_shr:1 row_mask:0xf bank_mask:0xf
	v_pk_fma_f32 v[6:7], v[58:59], v[108:109], v[66:67]
	v_pk_fma_f32 v[16:17], v[150:151], v[36:37], v[16:17]
	v_pk_fma_f32 v[6:7], v[48:49], v[104:105], v[6:7]
	v_mul_f32_e32 v10, v10, v18
	v_pk_fma_f32 v[6:7], v[184:185], v[52:53], v[6:7]
	v_mul_f32_e32 v10, v16, v10
	v_add_f32_e32 v16, 1.0, v19
	v_mul_f32_e32 v18, 0xbfb8aa3b, v6
	v_mul_f32_e32 v19, 0xbfb8aa3b, v7
	v_rcp_f32_e32 v16, v16
	v_exp_f32_e32 v18, v18
	v_exp_f32_e32 v19, v19
	v_mov_b32_dpp v192, v220 row_ror:2 row_mask:0xf bank_mask:0xf bound_ctrl:1
	v_mul_f32_e32 v11, v11, v16
	v_add_f32_e32 v16, 1.0, v18
	v_add_f32_e32 v18, 1.0, v19
	v_mov_b32_dpp v193, v221 row_ror:2 row_mask:0xf bank_mask:0xf bound_ctrl:1
; __device__ __forceinline__ unsigned cvt_pk_bf16(float lo, float hi) { unsigned r; asm volatile("v_cvt_pk_bf16_f32 %0, %1, %2" : "=v"(r) : "v"(lo), "v"(hi)); return r; }
; __device__ __forceinline__ float fexp2(float x) { return __builtin_amdgcn_exp2f(x); }
; __device__ __forceinline__ float frcp(float x) { return __builtin_amdgcn_rcpf(x); }
; __device__ __forceinline__ float dpp_shr1(float old, float src) { return __int_as_float(__builtin_amdgcn_update_dpp(__float_as_int(old), __float_as_int(src), 0x111, 0xf, 0xf, false)); }
; __device__ __forceinline__ float dpp_shr2(float old, float src) { return __int_as_float(__builtin_amdgcn_update_dpp(__float_as_int(old), __float_as_int(src), 0x112, 0xf, 0xf, false)); }
; __device__ __forceinline__ float dpp_ror1(float src) { return __int_as_float(__builtin_amdgcn_mov_dpp(__float_as_int(src), 0x121, 0xf, 0xf, true)); }
; __device__ __forceinline__ float dpp_ror2(float src) { return __int_as_float(__builtin_amdgcn_mov_dpp(__float_as_int(src), 0x122, 0xf, 0xf, true)); }
;     __device__ __forceinline__ void operator()(f32x4 (&acc)[2][2][4][2], const Unit& u, int wr, int wc, int fr, int fq) const {
;     ...
;             for (int n = 0; n < 2; ++n) {
;     ...
;                 const f32x4 wg0 = CQ4(0, 0), wg1 = CQ4(0, 1), wg2 = CQ4(0, 2), bg = CQ4(0, 3);
;                 const f32x4 wv0 = CQ4(1, 0), wv1 = CQ4(1, 1), wv2 = CQ4(1, 2), bv = CQ4(1, 3);
;     ...
;                 f32x4 pg1 = {0.f, 0.f, 0.f, 0.f}, pg2 = pg1, pv1 = pg1, pv2 = pg1;
; #pragma unroll
;                 for (int m = 0; m < 4; ++m) {
;                     const f32x4 zg = acc[ai][0][m][n], zv = acc[ai][1][m][n];
;                     f32x4 g1, g2, v1, v2;
; #pragma unroll
;                     for (int j = 0; j < 4; ++j) { g1[j] = dpp_shr1(pg1[j], zg[j]); g2[j] = dpp_shr2(pg2[j], zg[j]); v1[j] = dpp_shr1(pv1[j], zv[j]); v2[j] = dpp_shr2(pv2[j], zv[j]);
;                         pg1[j] = dpp_ror1(zg[j]); pg2[j] = dpp_ror2(zg[j]); pv1[j] = dpp_ror1(zv[j]); pv2[j] = dpp_ror2(zv[j]); }
;                     const f32x4 cg_ = bg + wg0 * g2 + wg1 * g1 + wg2 * zg, cv_ = bv + wv0 * v2 + wv1 * v1 + wv2 * zv;
;                     float o[4];
; #pragma unroll
;                     for (int j = 0; j < 4; ++j) o[j] = cg_[j] * frcp(1.0f + fexp2(-1.4426950409f * cg_[j])) * cv_[j];
;                     pk[m][n][0] = cvt_pk_bf16(o[0], o[1]); pk[m][n][1] = cvt_pk_bf16(o[2], o[3]);
	v_rcp_f32_e32 v16, v16
	v_rcp_f32_e32 v18, v18
	v_mov_b32_dpp v112, v220 row_ror:1 row_mask:0xf bank_mask:0xf bound_ctrl:1
	v_mov_b32_dpp v113, v221 row_ror:1 row_mask:0xf bank_mask:0xf bound_ctrl:1
	v_mov_b32_dpp v192, v160 row_shr:2 row_mask:0xf bank_mask:0xf
	v_mov_b32_dpp v193, v161 row_shr:2 row_mask:0xf bank_mask:0xf
	v_mov_b32_dpp v112, v160 row_shr:1 row_mask:0xf bank_mask:0xf
	v_mov_b32_dpp v113, v161 row_shr:1 row_mask:0xf bank_mask:0xf
	v_pk_fma_f32 v[14:15], v[56:57], v[192:193], v[64:65]
	v_mul_f32_e32 v11, v17, v11
	v_pk_fma_f32 v[14:15], v[40:41], v[112:113], v[14:15]
	v_mul_f32_e32 v6, v6, v16
	v_pk_fma_f32 v[14:15], v[160:161], v[42:43], v[14:15]
	v_mul_f32_e32 v7, v7, v18
	v_mul_f32_e32 v6, v14, v6
	v_mul_f32_e32 v7, v15, v7
	v_cvt_pk_bf16_f32 v16, v10, v11
	v_mov_b32_e32 v10, v2
	v_mov_b32_e32 v11, v2
	v_cvt_pk_bf16_f32 v17, v6, v7
	v_lshlrev_b32_e32 v100, 16, v86
	v_and_b32_e32 v101, 0xffff0000, v86
	v_lshlrev_b32_e32 v150, 16, v98
	v_and_b32_e32 v151, 0xffff0000, v98
	v_mov_b32_e32 v6, v2
	v_mov_b32_dpp v10, v156 row_shr:2 row_mask:0xf bank_mask:0xf
	v_mov_b32_e32 v7, v2
	v_mov_b32_dpp v11, v157 row_shr:2 row_mask:0xf bank_mask:0xf
	v_mov_b32_e32 v190, v2
	v_mov_b32_e32 v191, v2
	v_lshlrev_b32_e32 v112, 16, v87
	v_and_b32_e32 v113, 0xffff0000, v87
	v_lshlrev_b32_e32 v108, 16, v90
	v_and_b32_e32 v109, 0xffff0000, v90
	v_lshlrev_b32_e32 v160, 16, v99
	v_and_b32_e32 v161, 0xffff0000, v99
	v_mov_b32_dpp v6, v156 row_shr:1 row_mask:0xf bank_mask:0xf
	v_mov_b32_dpp v7, v157 row_shr:1 row_mask:0xf bank_mask:0xf
	v_mov_b32_e32 v188, v2
	v_mov_b32_dpp v190, v158 row_shr:2 row_mask:0xf bank_mask:0xf
	v_mov_b32_e32 v189, v2
	v_mov_b32_dpp v191, v159 row_shr:2 row_mask:0xf bank_mask:0xf
	v_pk_fma_f32 v[10:11], v[100:101], v[10:11], v[150:151]
	v_lshlrev_b32_e32 v96, 16, v91
	v_and_b32_e32 v97, 0xffff0000, v91
	v_lshlrev_b32_e32 v92, 16, v94
	v_and_b32_e32 v93, 0xffff0000, v94
	v_mov_b32_dpp v188, v158 row_shr:1 row_mask:0xf bank_mask:0xf
	v_mov_b32_dpp v189, v159 row_shr:1 row_mask:0xf bank_mask:0xf
	v_pk_fma_f32 v[190:191], v[112:113], v[190:191], v[160:161]
	v_pk_fma_f32 v[6:7], v[108:109], v[6:7], v[10:11]
	v_lshlrev_b32_e32 v104, 16, v95
	v_and_b32_e32 v105, 0xffff0000, v95
	v_pk_fma_f32 v[10:11], v[96:97], v[188:189], v[190:191]
	v_pk_fma_f32 v[6:7], v[156:157], v[92:93], v[6:7]
	v_mov_b32_dpp v218, v158 row_ror:1 row_mask:0xf bank_mask:0xf bound_ctrl:1
	v_mov_b32_dpp v220, v158 row_ror:2 row_mask:0xf bank_mask:0xf bound_ctrl:1
	v_pk_fma_f32 v[10:11], v[158:159], v[104:105], v[10:11]
	v_mul_f32_e32 v158, 0xbfb8aa3b, v6
	v_mov_b32_e32 v18, v2
	v_mov_b32_e32 v19, v2
	v_mov_b32_e32 v194, v2
	v_mov_b32_e32 v195, v2
	v_exp_f32_e32 v158, v158
	v_lshlrev_b32_e32 v94, 16, v102
	v_and_b32_e32 v95, 0xffff0000, v102
	v_lshlrev_b32_e32 v98, 16, v103
	v_and_b32_e32 v99, 0xffff0000, v103
	v_lshlrev_b32_e32 v86, 16, v106
	v_and_b32_e32 v87, 0xffff0000, v106
	v_lshlrev_b32_e32 v88, 16, v107
	v_and_b32_e32 v89, 0xffff0000, v107
	v_lshlrev_b32_e32 v102, 16, v114
	v_and_b32_e32 v103, 0xffff0000, v114
	v_lshlrev_b32_e32 v106, 16, v115
	v_and_b32_e32 v107, 0xffff0000, v115
	v_mov_b32_e32 v14, v2
	v_mov_b32_dpp v18, v152 row_shr:2 row_mask:0xf bank_mask:0xf
	v_mov_b32_e32 v15, v2
	v_mov_b32_dpp v19, v153 row_shr:2 row_mask:0xf bank_mask:0xf
	v_mov_b32_e32 v192, v2
	v_mov_b32_dpp v194, v154 row_shr:2 row_mask:0xf bank_mask:0xf
	v_mov_b32_e32 v193, v2
	v_mov_b32_dpp v195, v155 row_shr:2 row_mask:0xf bank_mask:0xf
	v_lshlrev_b32_e32 v84, 16, v110
	v_and_b32_e32 v85, 0xffff0000, v110
	v_lshlrev_b32_e32 v90, 16, v111
	v_and_b32_e32 v91, 0xffff0000, v111
	v_mov_b32_dpp v14, v152 row_shr:1 row_mask:0xf bank_mask:0xf
	v_mov_b32_dpp v110, v156 row_ror:1 row_mask:0xf bank_mask:0xf bound_ctrl:1
	v_mov_b32_dpp v114, v156 row_ror:2 row_mask:0xf bank_mask:0xf bound_ctrl:1
	v_mov_b32_dpp v15, v153 row_shr:1 row_mask:0xf bank_mask:0xf
	v_mov_b32_dpp v111, v157 row_ror:1 row_mask:0xf bank_mask:0xf bound_ctrl:1
	v_mov_b32_dpp v115, v157 row_ror:2 row_mask:0xf bank_mask:0xf bound_ctrl:1
	v_mov_b32_dpp v192, v154 row_shr:1 row_mask:0xf bank_mask:0xf
	v_mov_b32_dpp v193, v155 row_shr:1 row_mask:0xf bank_mask:0xf
	v_pk_fma_f32 v[156:157], v[98:99], v[194:195], v[106:107]
	v_pk_fma_f32 v[18:19], v[94:95], v[18:19], v[102:103]
	v_mov_b32_dpp v222, v154 row_ror:1 row_mask:0xf bank_mask:0xf bound_ctrl:1
	v_pk_fma_f32 v[14:15], v[86:87], v[14:15], v[18:19]
	v_pk_fma_f32 v[18:19], v[88:89], v[192:193], v[156:157]
	v_mov_b32_dpp v224, v154 row_ror:2 row_mask:0xf bank_mask:0xf bound_ctrl:1
	v_pk_fma_f32 v[18:19], v[154:155], v[90:91], v[18:19]
	v_add_f32_e32 v154, 1.0, v158
	v_mov_b32_dpp v223, v155 row_ror:1 row_mask:0xf bank_mask:0xf bound_ctrl:1
	v_mov_b32_dpp v225, v155 row_ror:2 row_mask:0xf bank_mask:0xf bound_ctrl:1
	v_rcp_f32_e32 v154, v154
	v_mul_f32_e32 v155, 0xbfb8aa3b, v7
	v_exp_f32_e32 v155, v155
	v_pk_fma_f32 v[14:15], v[152:153], v[84:85], v[14:15]
	v_mul_f32_e32 v6, v6, v154
	v_mov_b32_dpp v184, v152 row_ror:1 row_mask:0xf bank_mask:0xf bound_ctrl:1
	v_mov_b32_dpp v186, v152 row_ror:2 row_mask:0xf bank_mask:0xf bound_ctrl:1
	v_mov_b32_dpp v185, v153 row_ror:1 row_mask:0xf bank_mask:0xf bound_ctrl:1
	v_mov_b32_dpp v187, v153 row_ror:2 row_mask:0xf bank_mask:0xf bound_ctrl:1
	v_mul_f32_e32 v6, v14, v6
	v_add_f32_e32 v14, 1.0, v155
	v_mul_f32_e32 v152, 0xbfb8aa3b, v10
	v_mul_f32_e32 v153, 0xbfb8aa3b, v11
	v_mov_b32_dpp v114, v216 row_shr:2 row_mask:0xf bank_mask:0xf
	v_mov_b32_dpp v115, v217 row_shr:2 row_mask:0xf bank_mask:0xf
	v_rcp_f32_e32 v14, v14
	v_exp_f32_e32 v152, v152
	v_exp_f32_e32 v153, v153
	v_mov_b32_dpp v110, v216 row_shr:1 row_mask:0xf bank_mask:0xf
; __device__ __forceinline__ unsigned cvt_pk_bf16(float lo, float hi) { unsigned r; asm volatile("v_cvt_pk_bf16_f32 %0, %1, %2" : "=v"(r) : "v"(lo), "v"(hi)); return r; }
; __device__ __forceinline__ float fexp2(float x) { return __builtin_amdgcn_exp2f(x); }
; __device__ __forceinline__ float frcp(float x) { return __builtin_amdgcn_rcpf(x); }
; __device__ __forceinline__ float dpp_shr1(float old, float src) { return __int_as_float(__builtin_amdgcn_update_dpp(__float_as_int(old), __float_as_int(src), 0x111, 0xf, 0xf, false)); }
; __device__ __forceinline__ float dpp_shr2(float old, float src) { return __int_as_float(__builtin_amdgcn_update_dpp(__float_as_int(old), __float_as_int(src), 0x112, 0xf, 0xf, false)); }
; __device__ __forceinline__ float dpp_ror1(float src) { return __int_as_float(__builtin_amdgcn_mov_dpp(__float_as_int(src), 0x121, 0xf, 0xf, true)); }
; __device__ __forceinline__ float dpp_ror2(float src) { return __int_as_float(__builtin_amdgcn_mov_dpp(__float_as_int(src), 0x122, 0xf, 0xf, true)); }
;     __device__ __forceinline__ void operator()(f32x4 (&acc)[2][2][4][2], const Unit& u, int wr, int wc, int fr, int fq) const {
;     ...
;                 for (int m = 0; m < 4; ++m) {
;                     const f32x4 zg = acc[ai][0][m][n], zv = acc[ai][1][m][n];
;                     f32x4 g1, g2, v1, v2;
; #pragma unroll
;                     for (int j = 0; j < 4; ++j) { g1[j] = dpp_shr1(pg1[j], zg[j]); g2[j] = dpp_shr2(pg2[j], zg[j]); v1[j] = dpp_shr1(pv1[j], zv[j]); v2[j] = dpp_shr2(pv2[j], zv[j]);
;                         pg1[j] = dpp_ror1(zg[j]); pg2[j] = dpp_ror2(zg[j]); pv1[j] = dpp_ror1(zv[j]); pv2[j] = dpp_ror2(zv[j]); }
;                     const f32x4 cg_ = bg + wg0 * g2 + wg1 * g1 + wg2 * zg, cv_ = bv + wv0 * v2 + wv1 * v1 + wv2 * zv;
;                     float o[4];
; #pragma unroll
;                     for (int j = 0; j < 4; ++j) o[j] = cg_[j] * frcp(1.0f + fexp2(-1.4426950409f * cg_[j])) * cv_[j];
;                     pk[m][n][0] = cvt_pk_bf16(o[0], o[1]); pk[m][n][1] = cvt_pk_bf16(o[2], o[3]);
	v_mov_b32_dpp v111, v217 row_shr:1 row_mask:0xf bank_mask:0xf
	v_pk_fma_f32 v[114:115], v[100:101], v[114:115], v[150:151]
	v_mul_f32_e32 v7, v7, v14
	v_pk_fma_f32 v[110:111], v[108:109], v[110:111], v[114:115]
	v_add_f32_e32 v14, 1.0, v152
	v_pk_fma_f32 v[110:111], v[216:217], v[92:93], v[110:111]
	v_add_f32_e32 v152, 1.0, v153
	v_mul_f32_e32 v192, 0xbfb8aa3b, v110
	v_exp_f32_e32 v192, v192
	v_rcp_f32_e32 v14, v14
	v_rcp_f32_e32 v152, v152
	v_mov_b32_dpp v186, v210 row_shr:2 row_mask:0xf bank_mask:0xf
	v_mov_b32_dpp v187, v211 row_shr:2 row_mask:0xf bank_mask:0xf
	v_mov_b32_dpp v184, v210 row_shr:1 row_mask:0xf bank_mask:0xf
	s_setprio 0
	v_mov_b32_dpp v185, v211 row_shr:1 row_mask:0xf bank_mask:0xf
	v_pk_fma_f32 v[186:187], v[94:95], v[186:187], v[102:103]
	v_mov_b32_dpp v221, v159 row_ror:2 row_mask:0xf bank_mask:0xf bound_ctrl:1
	v_pk_fma_f32 v[184:185], v[86:87], v[184:185], v[186:187]
	v_add_f32_e32 v186, 1.0, v192
	v_mul_f32_e32 v10, v10, v14
	v_mul_f32_e32 v11, v11, v152
	v_rcp_f32_e32 v186, v186
	v_mul_f32_e32 v187, 0xbfb8aa3b, v111
	v_mov_b32_dpp v219, v159 row_ror:1 row_mask:0xf bank_mask:0xf bound_ctrl:1
	v_mul_f32_e32 v7, v15, v7
	v_mul_f32_e32 v10, v18, v10
	v_mul_f32_e32 v11, v19, v11
	v_mov_b32_dpp v18, v216 row_ror:2 row_mask:0xf bank_mask:0xf bound_ctrl:1
	v_mov_b32_dpp v19, v217 row_ror:2 row_mask:0xf bank_mask:0xf bound_ctrl:1
	v_mov_b32_dpp v220, v214 row_shr:2 row_mask:0xf bank_mask:0xf
	v_mov_b32_dpp v221, v215 row_shr:2 row_mask:0xf bank_mask:0xf
	v_exp_f32_e32 v187, v187
	v_cvt_pk_bf16_f32 v6, v6, v7
	v_cvt_pk_bf16_f32 v7, v10, v11
	v_mov_b32_dpp v14, v216 row_ror:1 row_mask:0xf bank_mask:0xf bound_ctrl:1
	v_mov_b32_dpp v15, v217 row_ror:1 row_mask:0xf bank_mask:0xf bound_ctrl:1
	v_mov_b32_dpp v218, v214 row_shr:1 row_mask:0xf bank_mask:0xf
	v_mov_b32_dpp v219, v215 row_shr:1 row_mask:0xf bank_mask:0xf
	v_pk_fma_f32 v[10:11], v[112:113], v[220:221], v[160:161]
	v_mov_b32_dpp v18, v208 row_shr:2 row_mask:0xf bank_mask:0xf
	v_mov_b32_dpp v19, v209 row_shr:2 row_mask:0xf bank_mask:0xf
	v_mov_b32_dpp v158, v214 row_ror:2 row_mask:0xf bank_mask:0xf bound_ctrl:1
	v_mov_b32_dpp v159, v215 row_ror:2 row_mask:0xf bank_mask:0xf bound_ctrl:1
	v_pk_fma_f32 v[10:11], v[96:97], v[218:219], v[10:11]
	v_mov_b32_dpp v14, v208 row_shr:1 row_mask:0xf bank_mask:0xf
	v_mov_b32_dpp v15, v209 row_shr:1 row_mask:0xf bank_mask:0xf
	v_pk_fma_f32 v[18:19], v[100:101], v[18:19], v[150:151]
	v_mov_b32_dpp v156, v214 row_ror:1 row_mask:0xf bank_mask:0xf bound_ctrl:1
	v_mov_b32_dpp v157, v215 row_ror:1 row_mask:0xf bank_mask:0xf bound_ctrl:1
	v_pk_fma_f32 v[10:11], v[214:215], v[104:105], v[10:11]
	v_pk_fma_f32 v[184:185], v[210:211], v[84:85], v[184:185]
	v_mul_f32_e32 v110, v110, v186
	v_mov_b32_dpp v158, v206 row_shr:2 row_mask:0xf bank_mask:0xf
	v_mov_b32_dpp v159, v207 row_shr:2 row_mask:0xf bank_mask:0xf
	v_pk_fma_f32 v[14:15], v[108:109], v[14:15], v[18:19]
	v_mul_f32_e32 v110, v184, v110
	v_add_f32_e32 v184, 1.0, v187
	v_mul_f32_e32 v186, 0xbfb8aa3b, v10
	v_mov_b32_dpp v156, v206 row_shr:1 row_mask:0xf bank_mask:0xf
	v_mov_b32_dpp v157, v207 row_shr:1 row_mask:0xf bank_mask:0xf
	v_pk_fma_f32 v[158:159], v[112:113], v[158:159], v[160:161]
	v_pk_fma_f32 v[14:15], v[208:209], v[92:93], v[14:15]
	v_rcp_f32_e32 v184, v184
	v_exp_f32_e32 v186, v186
	v_mul_f32_e32 v187, 0xbfb8aa3b, v11
	v_pk_fma_f32 v[18:19], v[96:97], v[156:157], v[158:159]
	v_mul_f32_e32 v158, 0xbfb8aa3b, v14
	v_exp_f32_e32 v187, v187
	v_exp_f32_e32 v158, v158
	v_mov_b32_dpp v154, v210 row_ror:2 row_mask:0xf bank_mask:0xf bound_ctrl:1
	v_mov_b32_dpp v155, v211 row_ror:2 row_mask:0xf bank_mask:0xf bound_ctrl:1
	v_mov_b32_dpp v190, v212 row_ror:2 row_mask:0xf bank_mask:0xf bound_ctrl:1
	v_mov_b32_dpp v191, v213 row_ror:2 row_mask:0xf bank_mask:0xf bound_ctrl:1
	v_mov_b32_dpp v152, v210 row_ror:1 row_mask:0xf bank_mask:0xf bound_ctrl:1
	v_mov_b32_dpp v153, v211 row_ror:1 row_mask:0xf bank_mask:0xf bound_ctrl:1
	v_mov_b32_dpp v188, v212 row_ror:1 row_mask:0xf bank_mask:0xf bound_ctrl:1
	v_mov_b32_dpp v189, v213 row_ror:1 row_mask:0xf bank_mask:0xf bound_ctrl:1
	v_mov_b32_dpp v154, v202 row_shr:2 row_mask:0xf bank_mask:0xf
	v_mov_b32_dpp v155, v203 row_shr:2 row_mask:0xf bank_mask:0xf
	v_mov_b32_dpp v190, v204 row_shr:2 row_mask:0xf bank_mask:0xf
	v_mov_b32_dpp v191, v205 row_shr:2 row_mask:0xf bank_mask:0xf
	v_mul_f32_e32 v111, v111, v184
	v_add_f32_e32 v184, 1.0, v186
	v_mov_b32_dpp v152, v202 row_shr:1 row_mask:0xf bank_mask:0xf
	v_mov_b32_dpp v153, v203 row_shr:1 row_mask:0xf bank_mask:0xf
	v_mov_b32_dpp v188, v204 row_shr:1 row_mask:0xf bank_mask:0xf
	v_mov_b32_dpp v189, v205 row_shr:1 row_mask:0xf bank_mask:0xf
	v_pk_fma_f32 v[156:157], v[98:99], v[190:191], v[106:107]
	v_pk_fma_f32 v[154:155], v[94:95], v[154:155], v[102:103]
	v_rcp_f32_e32 v184, v184
	v_add_f32_e32 v186, 1.0, v187
	v_pk_fma_f32 v[152:153], v[86:87], v[152:153], v[154:155]
	v_pk_fma_f32 v[154:155], v[88:89], v[188:189], v[156:157]
	v_add_f32_e32 v156, 1.0, v158
	v_mov_b32_dpp v224, v212 row_shr:2 row_mask:0xf bank_mask:0xf
	v_mov_b32_dpp v225, v213 row_shr:2 row_mask:0xf bank_mask:0xf
	v_rcp_f32_e32 v186, v186
	v_rcp_f32_e32 v156, v156
	v_mul_f32_e32 v157, 0xbfb8aa3b, v15
	v_mov_b32_dpp v222, v212 row_shr:1 row_mask:0xf bank_mask:0xf
	v_mov_b32_dpp v223, v213 row_shr:1 row_mask:0xf bank_mask:0xf
	v_pk_fma_f32 v[114:115], v[98:99], v[224:225], v[106:107]
	v_exp_f32_e32 v157, v157
	v_pk_fma_f32 v[114:115], v[88:89], v[222:223], v[114:115]
	v_mul_f32_e32 v10, v10, v184
	v_pk_fma_f32 v[114:115], v[212:213], v[90:91], v[114:115]
	v_pk_fma_f32 v[18:19], v[206:207], v[104:105], v[18:19]
	v_mul_f32_e32 v114, v114, v10
; __device__ __forceinline__ unsigned cvt_pk_bf16(float lo, float hi) { unsigned r; asm volatile("v_cvt_pk_bf16_f32 %0, %1, %2" : "=v"(r) : "v"(lo), "v"(hi)); return r; }
; __device__ __forceinline__ float fexp2(float x) { return __builtin_amdgcn_exp2f(x); }
; __device__ __forceinline__ float frcp(float x) { return __builtin_amdgcn_rcpf(x); }
; __device__ __forceinline__ float dpp_shr1(float old, float src) { return __int_as_float(__builtin_amdgcn_update_dpp(__float_as_int(old), __float_as_int(src), 0x111, 0xf, 0xf, false)); }
; __device__ __forceinline__ float dpp_shr2(float old, float src) { return __int_as_float(__builtin_amdgcn_update_dpp(__float_as_int(old), __float_as_int(src), 0x112, 0xf, 0xf, false)); }
; __device__ __forceinline__ float dpp_ror1(float src) { return __int_as_float(__builtin_amdgcn_mov_dpp(__float_as_int(src), 0x121, 0xf, 0xf, true)); }
; __device__ __forceinline__ float dpp_ror2(float src) { return __int_as_float(__builtin_amdgcn_mov_dpp(__float_as_int(src), 0x122, 0xf, 0xf, true)); }
;     __device__ __forceinline__ void operator()(f32x4 (&acc)[2][2][4][2], const Unit& u, int wr, int wc, int fr, int fq) const {
;     ...
;                 for (int m = 0; m < 4; ++m) {
;                     const f32x4 zg = acc[ai][0][m][n], zv = acc[ai][1][m][n];
;                     f32x4 g1, g2, v1, v2;
; #pragma unroll
;                     for (int j = 0; j < 4; ++j) { g1[j] = dpp_shr1(pg1[j], zg[j]); g2[j] = dpp_shr2(pg2[j], zg[j]); v1[j] = dpp_shr1(pv1[j], zv[j]); v2[j] = dpp_shr2(pv2[j], zv[j]);
;                         pg1[j] = dpp_ror1(zg[j]); pg2[j] = dpp_ror2(zg[j]); pv1[j] = dpp_ror1(zv[j]); pv2[j] = dpp_ror2(zv[j]); }
;                     const f32x4 cg_ = bg + wg0 * g2 + wg1 * g1 + wg2 * zg, cv_ = bv + wv0 * v2 + wv1 * v1 + wv2 * zv;
;                     float o[4];
; #pragma unroll
;                     for (int j = 0; j < 4; ++j) o[j] = cg_[j] * frcp(1.0f + fexp2(-1.4426950409f * cg_[j])) * cv_[j];
;                     pk[m][n][0] = cvt_pk_bf16(o[0], o[1]); pk[m][n][1] = cvt_pk_bf16(o[2], o[3]);
;                 }
;             }
; #pragma unroll
;             for (int m = 0; m < 4; ++m) { u32x4 w; w.x = pk[m][0][0]; w.y = pk[m][0][1]; w.z = pk[m][1][0]; w.w = pk[m][1][1];
;                 *(u32x4*)(act + (size_t)(row0 + ai * HALF + m * 16) * 2816 + f0) = w; }
	v_mul_f32_e32 v10, v11, v186
	v_pk_fma_f32 v[152:153], v[202:203], v[84:85], v[152:153]
	v_mul_f32_e32 v14, v14, v156
	v_mul_f32_e32 v11, v115, v10
	v_mul_f32_e32 v14, v152, v14
	v_add_f32_e32 v152, 1.0, v157
	v_mul_f32_e32 v156, 0xbfb8aa3b, v18
	v_mul_f32_e32 v157, 0xbfb8aa3b, v19
	v_mul_f32_e32 v111, v185, v111
	v_cvt_pk_bf16_f32 v10, v110, v111
	v_cvt_pk_bf16_f32 v11, v114, v11
	v_mov_b32_dpp v114, v208 row_ror:2 row_mask:0xf bank_mask:0xf bound_ctrl:1
	v_mov_b32_dpp v115, v209 row_ror:2 row_mask:0xf bank_mask:0xf bound_ctrl:1
	v_rcp_f32_e32 v152, v152
	v_exp_f32_e32 v156, v156
	v_exp_f32_e32 v157, v157
	v_mov_b32_dpp v110, v208 row_ror:1 row_mask:0xf bank_mask:0xf bound_ctrl:1
	v_mov_b32_dpp v111, v209 row_ror:1 row_mask:0xf bank_mask:0xf bound_ctrl:1
	v_mov_b32_dpp v114, v142 row_shr:2 row_mask:0xf bank_mask:0xf
	v_mov_b32_dpp v115, v143 row_shr:2 row_mask:0xf bank_mask:0xf
	v_mov_b32_dpp v110, v142 row_shr:1 row_mask:0xf bank_mask:0xf
	v_mov_b32_dpp v111, v143 row_shr:1 row_mask:0xf bank_mask:0xf
	v_pk_fma_f32 v[114:115], v[100:101], v[114:115], v[150:151]
	v_mul_f32_e32 v15, v15, v152
	v_pk_fma_f32 v[110:111], v[108:109], v[110:111], v[114:115]
	v_add_f32_e32 v152, 1.0, v156
	v_add_f32_e32 v156, 1.0, v157
	v_pk_fma_f32 v[110:111], v[142:143], v[92:93], v[110:111]
	v_rcp_f32_e32 v152, v152
	v_rcp_f32_e32 v156, v156
	v_mul_f32_e32 v142, 0xbfb8aa3b, v110
	v_mov_b32_dpp v212, v204 row_ror:2 row_mask:0xf bank_mask:0xf bound_ctrl:1
	v_mov_b32_dpp v213, v205 row_ror:2 row_mask:0xf bank_mask:0xf bound_ctrl:1
	v_exp_f32_e32 v142, v142
	v_mov_b32_dpp v210, v204 row_ror:1 row_mask:0xf bank_mask:0xf bound_ctrl:1
	v_mov_b32_dpp v211, v205 row_ror:1 row_mask:0xf bank_mask:0xf bound_ctrl:1
	v_mov_b32_dpp v212, v138 row_shr:2 row_mask:0xf bank_mask:0xf
	v_mov_b32_dpp v213, v139 row_shr:2 row_mask:0xf bank_mask:0xf
	v_mov_b32_dpp v210, v138 row_shr:1 row_mask:0xf bank_mask:0xf
	v_mov_b32_dpp v211, v139 row_shr:1 row_mask:0xf bank_mask:0xf
	v_pk_fma_f32 v[114:115], v[98:99], v[212:213], v[106:107]
	v_mov_b32_dpp v194, v206 row_ror:2 row_mask:0xf bank_mask:0xf bound_ctrl:1
	v_mov_b32_dpp v195, v207 row_ror:2 row_mask:0xf bank_mask:0xf bound_ctrl:1
	v_pk_fma_f32 v[154:155], v[204:205], v[90:91], v[154:155]
	v_mul_f32_e32 v18, v18, v152
	v_mul_f32_e32 v19, v19, v156
	v_pk_fma_f32 v[114:115], v[88:89], v[210:211], v[114:115]
	v_mov_b32_dpp v192, v206 row_ror:1 row_mask:0xf bank_mask:0xf bound_ctrl:1
	v_mov_b32_dpp v193, v207 row_ror:1 row_mask:0xf bank_mask:0xf bound_ctrl:1
	v_mul_f32_e32 v15, v153, v15
	v_mul_f32_e32 v18, v154, v18
	v_mul_f32_e32 v19, v155, v19
	v_mov_b32_dpp v194, v140 row_shr:2 row_mask:0xf bank_mask:0xf
	v_mov_b32_dpp v195, v141 row_shr:2 row_mask:0xf bank_mask:0xf
	v_pk_fma_f32 v[114:115], v[138:139], v[90:91], v[114:115]
	v_add_f32_e32 v138, 1.0, v142
	v_mov_b32_dpp v186, v202 row_ror:2 row_mask:0xf bank_mask:0xf bound_ctrl:1
	v_mov_b32_dpp v187, v203 row_ror:2 row_mask:0xf bank_mask:0xf bound_ctrl:1
	v_cvt_pk_bf16_f32 v14, v14, v15
	v_cvt_pk_bf16_f32 v15, v18, v19
	v_mov_b32_dpp v192, v140 row_shr:1 row_mask:0xf bank_mask:0xf
	v_mov_b32_dpp v193, v141 row_shr:1 row_mask:0xf bank_mask:0xf
	v_pk_fma_f32 v[18:19], v[112:113], v[194:195], v[160:161]
	v_rcp_f32_e32 v138, v138
	s_setprio 1
	v_mul_f32_e32 v139, 0xbfb8aa3b, v111
	v_mov_b32_dpp v184, v202 row_ror:1 row_mask:0xf bank_mask:0xf bound_ctrl:1
	v_mov_b32_dpp v185, v203 row_ror:1 row_mask:0xf bank_mask:0xf bound_ctrl:1
	v_mov_b32_dpp v186, v136 row_shr:2 row_mask:0xf bank_mask:0xf
	v_mov_b32_dpp v187, v137 row_shr:2 row_mask:0xf bank_mask:0xf
	v_pk_fma_f32 v[18:19], v[96:97], v[192:193], v[18:19]
	v_exp_f32_e32 v139, v139
	v_mov_b32_dpp v184, v136 row_shr:1 row_mask:0xf bank_mask:0xf
	v_mov_b32_dpp v185, v137 row_shr:1 row_mask:0xf bank_mask:0xf
	v_pk_fma_f32 v[18:19], v[140:141], v[104:105], v[18:19]
	v_pk_fma_f32 v[140:141], v[94:95], v[186:187], v[102:103]
	v_mul_f32_e32 v110, v110, v138
	v_pk_fma_f32 v[140:141], v[86:87], v[184:185], v[140:141]
	v_mul_f32_e32 v138, 0xbfb8aa3b, v18
	v_pk_fma_f32 v[136:137], v[136:137], v[84:85], v[140:141]
	v_exp_f32_e32 v138, v138
	v_mul_f32_e32 v110, v136, v110
	v_add_f32_e32 v136, 1.0, v139
	v_rcp_f32_e32 v136, v136
	v_mul_f32_e32 v139, 0xbfb8aa3b, v19
	v_exp_f32_e32 v139, v139
	v_mov_b32_dpp v142, v132 row_ror:1 row_mask:0xf bank_mask:0xf bound_ctrl:1
	v_mul_f32_e32 v111, v111, v136
	v_add_f32_e32 v136, 1.0, v138
	v_rcp_f32_e32 v136, v136
	v_add_f32_e32 v138, 1.0, v139
	v_rcp_f32_e32 v138, v138
	v_mul_f32_e32 v111, v137, v111
	v_mul_f32_e32 v18, v18, v136
	v_mul_f32_e32 v114, v114, v18
	v_mul_f32_e32 v18, v19, v138
	v_mul_f32_e32 v19, v115, v18
	v_cvt_pk_bf16_f32 v18, v110, v111
	v_mov_b64_e32 v[110:111], s[16:17]
	v_cvt_pk_bf16_f32 v19, v114, v19
	v_mad_i64_i32 v[114:115], s[18:19], v176, s22, v[110:111]
	v_lshl_add_u64 v[114:115], v[114:115], 0, v[68:69]
	global_store_dwordx4 v[114:115], v[4:7], off
	v_mov_b32_e32 v136, v2
	v_mov_b32_e32 v137, v2
	v_mad_i64_i32 v[4:5], s[18:19], v249, s22, v[110:111]
	v_lshl_add_u64 v[4:5], v[4:5], 0, v[68:69]
	global_store_dwordx4 v[4:5], v[8:11], off
	v_mad_i64_i32 v[4:5], s[18:19], v250, s22, v[110:111]
	v_lshl_add_u64 v[4:5], v[4:5], 0, v[68:69]
	global_store_dwordx4 v[4:5], v[12:15], off
	v_mad_i64_i32 v[4:5], s[18:19], v251, s22, v[110:111]
	v_lshl_add_u64 v[4:5], v[4:5], 0, v[68:69]
	v_mov_b32_e32 v6, v2
	v_mov_b32_e32 v7, v2
	global_store_dwordx4 v[4:5], v[16:19], off
	v_mov_b32_e32 v4, v2
	v_mov_b32_dpp v6, v134 row_shr:2 row_mask:0xf bank_mask:0xf
	v_mov_b32_e32 v5, v2
	v_mov_b32_dpp v7, v135 row_shr:2 row_mask:0xf bank_mask:0xf
	v_mov_b32_dpp v4, v134 row_shr:1 row_mask:0xf bank_mask:0xf
; __device__ __forceinline__ unsigned cvt_pk_bf16(float lo, float hi) { unsigned r; asm volatile("v_cvt_pk_bf16_f32 %0, %1, %2" : "=v"(r) : "v"(lo), "v"(hi)); return r; }
; __device__ __forceinline__ float fexp2(float x) { return __builtin_amdgcn_exp2f(x); }
; __device__ __forceinline__ float frcp(float x) { return __builtin_amdgcn_rcpf(x); }
; __device__ __forceinline__ float dpp_shr1(float old, float src) { return __int_as_float(__builtin_amdgcn_update_dpp(__float_as_int(old), __float_as_int(src), 0x111, 0xf, 0xf, false)); }
; __device__ __forceinline__ float dpp_shr2(float old, float src) { return __int_as_float(__builtin_amdgcn_update_dpp(__float_as_int(old), __float_as_int(src), 0x112, 0xf, 0xf, false)); }
; __device__ __forceinline__ float dpp_ror1(float src) { return __int_as_float(__builtin_amdgcn_mov_dpp(__float_as_int(src), 0x121, 0xf, 0xf, true)); }
;     __device__ __forceinline__ void operator()(f32x4 (&acc)[2][2][4][2], const Unit& u, int wr, int wc, int fr, int fq) const {
;     ...
;         for (int ai = 0; ai < 2; ++ai) {
;             unsigned pk[4][2][2];
; #pragma unroll
;             for (int n = 0; n < 2; ++n) {
;     ...
;                 const f32x4 wg0 = CQ4(0, 0), wg1 = CQ4(0, 1), wg2 = CQ4(0, 2), bg = CQ4(0, 3);
;                 const f32x4 wv0 = CQ4(1, 0), wv1 = CQ4(1, 1), wv2 = CQ4(1, 2), bv = CQ4(1, 3);
;     ...
;                 f32x4 pg1 = {0.f, 0.f, 0.f, 0.f}, pg2 = pg1, pv1 = pg1, pv2 = pg1;
; #pragma unroll
;                 for (int m = 0; m < 4; ++m) {
;                     const f32x4 zg = acc[ai][0][m][n], zv = acc[ai][1][m][n];
;                     f32x4 g1, g2, v1, v2;
; #pragma unroll
;                     for (int j = 0; j < 4; ++j) { g1[j] = dpp_shr1(pg1[j], zg[j]); g2[j] = dpp_shr2(pg2[j], zg[j]); v1[j] = dpp_shr1(pv1[j], zv[j]); v2[j] = dpp_shr2(pv2[j], zv[j]);
;                         pg1[j] = dpp_ror1(zg[j]); pg2[j] = dpp_ror2(zg[j]); pv1[j] = dpp_ror1(zv[j]); pv2[j] = dpp_ror2(zv[j]); }
;                     const f32x4 cg_ = bg + wg0 * g2 + wg1 * g1 + wg2 * zg, cv_ = bv + wv0 * v2 + wv1 * v1 + wv2 * zv;
;                     float o[4];
; #pragma unroll
;                     for (int j = 0; j < 4; ++j) o[j] = cg_[j] * frcp(1.0f + fexp2(-1.4426950409f * cg_[j])) * cv_[j];
;                     pk[m][n][0] = cvt_pk_bf16(o[0], o[1]); pk[m][n][1] = cvt_pk_bf16(o[2], o[3]);
	v_mov_b32_dpp v5, v135 row_shr:1 row_mask:0xf bank_mask:0xf
	v_mov_b32_e32 v114, v2
	v_mov_b32_dpp v136, v132 row_shr:2 row_mask:0xf bank_mask:0xf
	v_mov_b32_e32 v115, v2
	v_mov_b32_dpp v137, v133 row_shr:2 row_mask:0xf bank_mask:0xf
	v_pk_fma_f32 v[6:7], v[50:51], v[6:7], v[62:63]
	v_mov_b32_dpp v114, v132 row_shr:1 row_mask:0xf bank_mask:0xf
	v_mov_b32_dpp v115, v133 row_shr:1 row_mask:0xf bank_mask:0xf
	v_pk_fma_f32 v[136:137], v[58:59], v[136:137], v[66:67]
	v_pk_fma_f32 v[4:5], v[54:55], v[4:5], v[6:7]
	v_pk_fma_f32 v[6:7], v[48:49], v[114:115], v[136:137]
	v_pk_fma_f32 v[4:5], v[134:135], v[44:45], v[4:5]
	v_mov_b32_dpp v152, v132 row_ror:2 row_mask:0xf bank_mask:0xf bound_ctrl:1
	v_pk_fma_f32 v[6:7], v[132:133], v[52:53], v[6:7]
	v_mul_f32_e32 v132, 0xbfb8aa3b, v4
	v_exp_f32_e32 v132, v132
	v_mov_b32_e32 v10, v2
	v_mov_b32_e32 v11, v2
	v_mov_b32_e32 v140, v2
	v_mov_b32_e32 v141, v2
	v_mov_b32_e32 v8, v2
	v_mov_b32_dpp v10, v124 row_shr:2 row_mask:0xf bank_mask:0xf
	v_mov_b32_e32 v9, v2
	v_mov_b32_dpp v11, v125 row_shr:2 row_mask:0xf bank_mask:0xf
	v_mov_b32_e32 v138, v2
	v_mov_b32_dpp v140, v126 row_shr:2 row_mask:0xf bank_mask:0xf
	v_mov_b32_e32 v139, v2
	v_mov_b32_dpp v141, v127 row_shr:2 row_mask:0xf bank_mask:0xf
	v_mov_b32_dpp v8, v124 row_shr:1 row_mask:0xf bank_mask:0xf
	v_mov_b32_dpp v9, v125 row_shr:1 row_mask:0xf bank_mask:0xf
	v_mov_b32_dpp v138, v126 row_shr:1 row_mask:0xf bank_mask:0xf
	v_mov_b32_dpp v139, v127 row_shr:1 row_mask:0xf bank_mask:0xf
	v_pk_fma_f32 v[114:115], v[56:57], v[140:141], v[64:65]
	v_pk_fma_f32 v[10:11], v[46:47], v[10:11], v[60:61]
	v_mov_b32_dpp v14, v134 row_ror:2 row_mask:0xf bank_mask:0xf bound_ctrl:1
	v_pk_fma_f32 v[8:9], v[38:39], v[8:9], v[10:11]
	v_pk_fma_f32 v[10:11], v[40:41], v[138:139], v[114:115]
	v_add_f32_e32 v114, 1.0, v132
	v_rcp_f32_e32 v114, v114
	v_mul_f32_e32 v115, 0xbfb8aa3b, v5
	v_exp_f32_e32 v115, v115
	v_mov_b32_dpp v15, v135 row_ror:2 row_mask:0xf bank_mask:0xf bound_ctrl:1
	v_mov_b32_dpp v12, v134 row_ror:1 row_mask:0xf bank_mask:0xf bound_ctrl:1
	v_mov_b32_dpp v13, v135 row_ror:1 row_mask:0xf bank_mask:0xf bound_ctrl:1
	v_mov_b32_dpp v14, v182 row_shr:2 row_mask:0xf bank_mask:0xf
	v_mov_b32_dpp v15, v183 row_shr:2 row_mask:0xf bank_mask:0xf
	v_pk_fma_f32 v[8:9], v[124:125], v[36:37], v[8:9]
	v_mul_f32_e32 v4, v4, v114
	v_mov_b32_dpp v12, v182 row_shr:1 row_mask:0xf bank_mask:0xf
	v_mov_b32_dpp v13, v183 row_shr:1 row_mask:0xf bank_mask:0xf
	v_pk_fma_f32 v[14:15], v[50:51], v[14:15], v[62:63]
	v_mul_f32_e32 v4, v8, v4
	v_add_f32_e32 v8, 1.0, v115
	v_mul_f32_e32 v114, 0xbfb8aa3b, v6
	v_pk_fma_f32 v[12:13], v[54:55], v[12:13], v[14:15]
	v_rcp_f32_e32 v8, v8
	v_exp_f32_e32 v114, v114
	v_pk_fma_f32 v[12:13], v[182:183], v[44:45], v[12:13]
	v_mov_b32_dpp v18, v124 row_ror:2 row_mask:0xf bank_mask:0xf bound_ctrl:1
	v_mul_f32_e32 v138, 0xbfb8aa3b, v12
	v_exp_f32_e32 v138, v138
	v_mov_b32_dpp v19, v125 row_ror:2 row_mask:0xf bank_mask:0xf bound_ctrl:1
	v_mov_b32_dpp v16, v124 row_ror:1 row_mask:0xf bank_mask:0xf bound_ctrl:1
	v_mov_b32_dpp v17, v125 row_ror:1 row_mask:0xf bank_mask:0xf bound_ctrl:1
	v_mul_f32_e32 v5, v5, v8
	v_add_f32_e32 v8, 1.0, v114
	v_mov_b32_dpp v18, v162 row_shr:2 row_mask:0xf bank_mask:0xf
	v_mov_b32_dpp v19, v163 row_shr:2 row_mask:0xf bank_mask:0xf
	v_rcp_f32_e32 v8, v8
	v_mov_b32_dpp v16, v162 row_shr:1 row_mask:0xf bank_mask:0xf
	v_mov_b32_dpp v17, v163 row_shr:1 row_mask:0xf bank_mask:0xf
	v_pk_fma_f32 v[18:19], v[46:47], v[18:19], v[60:61]
	v_mov_b32_dpp v153, v133 row_ror:2 row_mask:0xf bank_mask:0xf bound_ctrl:1
	v_pk_fma_f32 v[16:17], v[38:39], v[16:17], v[18:19]
	v_add_f32_e32 v18, 1.0, v138
	v_rcp_f32_e32 v18, v18
	v_mul_f32_e32 v19, 0xbfb8aa3b, v13
	v_mov_b32_dpp v143, v133 row_ror:1 row_mask:0xf bank_mask:0xf bound_ctrl:1
	v_mov_b32_dpp v152, v180 row_shr:2 row_mask:0xf bank_mask:0xf
	v_mov_b32_dpp v153, v181 row_shr:2 row_mask:0xf bank_mask:0xf
	v_exp_f32_e32 v19, v19
	v_mul_f32_e32 v115, 0xbfb8aa3b, v7
	v_mul_f32_e32 v5, v9, v5
	v_mul_f32_e32 v6, v6, v8
	v_mov_b32_dpp v142, v180 row_shr:1 row_mask:0xf bank_mask:0xf
	v_mov_b32_dpp v143, v181 row_shr:1 row_mask:0xf bank_mask:0xf
	v_pk_fma_f32 v[8:9], v[58:59], v[152:153], v[66:67]
	v_exp_f32_e32 v115, v115
	v_pk_fma_f32 v[8:9], v[48:49], v[142:143], v[8:9]
	v_pk_fma_f32 v[16:17], v[162:163], v[36:37], v[16:17]
	v_pk_fma_f32 v[8:9], v[180:181], v[52:53], v[8:9]
	v_mul_f32_e32 v12, v12, v18
	v_mul_f32_e32 v12, v16, v12
	v_add_f32_e32 v16, 1.0, v19
	v_mul_f32_e32 v18, 0xbfb8aa3b, v8
	v_rcp_f32_e32 v16, v16
	v_exp_f32_e32 v18, v18
	v_mul_f32_e32 v19, 0xbfb8aa3b, v9
	v_add_f32_e32 v114, 1.0, v115
	v_exp_f32_e32 v19, v19
	v_rcp_f32_e32 v114, v114
	v_mul_f32_e32 v13, v13, v16
	v_add_f32_e32 v16, 1.0, v18
	v_mov_b32_dpp v156, v126 row_ror:2 row_mask:0xf bank_mask:0xf bound_ctrl:1
	v_mov_b32_dpp v157, v127 row_ror:2 row_mask:0xf bank_mask:0xf bound_ctrl:1
	v_rcp_f32_e32 v16, v16
	v_add_f32_e32 v18, 1.0, v19
	v_mov_b32_dpp v154, v126 row_ror:1 row_mask:0xf bank_mask:0xf bound_ctrl:1
	v_mov_b32_dpp v155, v127 row_ror:1 row_mask:0xf bank_mask:0xf bound_ctrl:1
	v_pk_fma_f32 v[10:11], v[126:127], v[42:43], v[10:11]
	s_setprio 0
	v_mul_f32_e32 v7, v7, v114
	v_mov_b32_dpp v156, v178 row_shr:2 row_mask:0xf bank_mask:0xf
	v_mov_b32_dpp v157, v179 row_shr:2 row_mask:0xf bank_mask:0xf
	v_rcp_f32_e32 v18, v18
	v_mul_f32_e32 v6, v10, v6
	v_mul_f32_e32 v7, v11, v7
	v_mov_b32_dpp v10, v182 row_ror:2 row_mask:0xf bank_mask:0xf bound_ctrl:1
	v_mov_b32_dpp v11, v183 row_ror:2 row_mask:0xf bank_mask:0xf bound_ctrl:1
	v_mov_b32_dpp v154, v178 row_shr:1 row_mask:0xf bank_mask:0xf
	v_mov_b32_dpp v155, v179 row_shr:1 row_mask:0xf bank_mask:0xf
; __device__ __forceinline__ unsigned cvt_pk_bf16(float lo, float hi) { unsigned r; asm volatile("v_cvt_pk_bf16_f32 %0, %1, %2" : "=v"(r) : "v"(lo), "v"(hi)); return r; }
; __device__ __forceinline__ float fexp2(float x) { return __builtin_amdgcn_exp2f(x); }
; __device__ __forceinline__ float frcp(float x) { return __builtin_amdgcn_rcpf(x); }
; __device__ __forceinline__ float dpp_shr1(float old, float src) { return __int_as_float(__builtin_amdgcn_update_dpp(__float_as_int(old), __float_as_int(src), 0x111, 0xf, 0xf, false)); }
; __device__ __forceinline__ float dpp_shr2(float old, float src) { return __int_as_float(__builtin_amdgcn_update_dpp(__float_as_int(old), __float_as_int(src), 0x112, 0xf, 0xf, false)); }
; __device__ __forceinline__ float dpp_ror1(float src) { return __int_as_float(__builtin_amdgcn_mov_dpp(__float_as_int(src), 0x121, 0xf, 0xf, true)); }
; __device__ __forceinline__ float dpp_ror2(float src) { return __int_as_float(__builtin_amdgcn_mov_dpp(__float_as_int(src), 0x122, 0xf, 0xf, true)); }
;     __device__ __forceinline__ void operator()(f32x4 (&acc)[2][2][4][2], const Unit& u, int wr, int wc, int fr, int fq) const {
;     ...
;                 for (int m = 0; m < 4; ++m) {
;                     const f32x4 zg = acc[ai][0][m][n], zv = acc[ai][1][m][n];
;                     f32x4 g1, g2, v1, v2;
; #pragma unroll
;                     for (int j = 0; j < 4; ++j) { g1[j] = dpp_shr1(pg1[j], zg[j]); g2[j] = dpp_shr2(pg2[j], zg[j]); v1[j] = dpp_shr1(pv1[j], zv[j]); v2[j] = dpp_shr2(pv2[j], zv[j]);
;                         pg1[j] = dpp_ror1(zg[j]); pg2[j] = dpp_ror2(zg[j]); pv1[j] = dpp_ror1(zv[j]); pv2[j] = dpp_ror2(zv[j]); }
;                     const f32x4 cg_ = bg + wg0 * g2 + wg1 * g1 + wg2 * zg, cv_ = bv + wv0 * v2 + wv1 * v1 + wv2 * zv;
;                     float o[4];
; #pragma unroll
;                     for (int j = 0; j < 4; ++j) o[j] = cg_[j] * frcp(1.0f + fexp2(-1.4426950409f * cg_[j])) * cv_[j];
;                     pk[m][n][0] = cvt_pk_bf16(o[0], o[1]); pk[m][n][1] = cvt_pk_bf16(o[2], o[3]);
	v_pk_fma_f32 v[14:15], v[56:57], v[156:157], v[64:65]
	v_cvt_pk_bf16_f32 v4, v4, v5
	v_cvt_pk_bf16_f32 v5, v6, v7
	v_mov_b32_dpp v6, v182 row_ror:1 row_mask:0xf bank_mask:0xf bound_ctrl:1
	v_mov_b32_dpp v7, v183 row_ror:1 row_mask:0xf bank_mask:0xf bound_ctrl:1
	v_pk_fma_f32 v[14:15], v[40:41], v[154:155], v[14:15]
	v_mov_b32_dpp v10, v148 row_shr:2 row_mask:0xf bank_mask:0xf
	v_mov_b32_dpp v11, v149 row_shr:2 row_mask:0xf bank_mask:0xf
	v_mov_b32_dpp v132, v180 row_ror:2 row_mask:0xf bank_mask:0xf bound_ctrl:1
	v_mov_b32_dpp v133, v181 row_ror:2 row_mask:0xf bank_mask:0xf bound_ctrl:1
	v_pk_fma_f32 v[14:15], v[178:179], v[42:43], v[14:15]
	v_mul_f32_e32 v8, v8, v16
	v_mov_b32_dpp v6, v148 row_shr:1 row_mask:0xf bank_mask:0xf
	v_mov_b32_dpp v7, v149 row_shr:1 row_mask:0xf bank_mask:0xf
	v_pk_fma_f32 v[10:11], v[50:51], v[10:11], v[62:63]
	v_mov_b32_dpp v126, v180 row_ror:1 row_mask:0xf bank_mask:0xf bound_ctrl:1
	v_mov_b32_dpp v127, v181 row_ror:1 row_mask:0xf bank_mask:0xf bound_ctrl:1
	v_mul_f32_e32 v13, v17, v13
	v_mul_f32_e32 v14, v14, v8
	v_mul_f32_e32 v8, v9, v18
	v_mov_b32_dpp v132, v146 row_shr:2 row_mask:0xf bank_mask:0xf
	v_mov_b32_dpp v133, v147 row_shr:2 row_mask:0xf bank_mask:0xf
	v_pk_fma_f32 v[6:7], v[54:55], v[6:7], v[10:11]
	v_mul_f32_e32 v9, v15, v8
	v_cvt_pk_bf16_f32 v8, v12, v13
	v_mov_b32_dpp v126, v146 row_shr:1 row_mask:0xf bank_mask:0xf
	v_mov_b32_dpp v127, v147 row_shr:1 row_mask:0xf bank_mask:0xf
	v_pk_fma_f32 v[12:13], v[58:59], v[132:133], v[66:67]
	v_pk_fma_f32 v[6:7], v[148:149], v[44:45], v[6:7]
	v_pk_fma_f32 v[10:11], v[48:49], v[126:127], v[12:13]
	v_mul_f32_e32 v126, 0xbfb8aa3b, v6
	v_exp_f32_e32 v126, v126
	v_mov_b32_dpp v124, v162 row_ror:2 row_mask:0xf bank_mask:0xf bound_ctrl:1
	v_mov_b32_dpp v125, v163 row_ror:2 row_mask:0xf bank_mask:0xf bound_ctrl:1
	v_mov_b32_dpp v114, v162 row_ror:1 row_mask:0xf bank_mask:0xf bound_ctrl:1
	v_mov_b32_dpp v115, v163 row_ror:1 row_mask:0xf bank_mask:0xf bound_ctrl:1
	v_mov_b32_dpp v124, v122 row_shr:2 row_mask:0xf bank_mask:0xf
	v_mov_b32_dpp v125, v123 row_shr:2 row_mask:0xf bank_mask:0xf
	v_mov_b32_dpp v114, v122 row_shr:1 row_mask:0xf bank_mask:0xf
	v_mov_b32_dpp v115, v123 row_shr:1 row_mask:0xf bank_mask:0xf
	v_pk_fma_f32 v[124:125], v[46:47], v[124:125], v[60:61]
	v_pk_fma_f32 v[10:11], v[146:147], v[52:53], v[10:11]
	v_pk_fma_f32 v[114:115], v[38:39], v[114:115], v[124:125]
	v_add_f32_e32 v124, 1.0, v126
	v_rcp_f32_e32 v124, v124
	v_mul_f32_e32 v125, 0xbfb8aa3b, v7
	v_exp_f32_e32 v125, v125
	v_pk_fma_f32 v[114:115], v[122:123], v[36:37], v[114:115]
	v_mul_f32_e32 v6, v6, v124
	v_mov_b32_dpp v18, v122 row_ror:1 row_mask:0xf bank_mask:0xf bound_ctrl:1
	v_mov_b32_dpp v138, v122 row_ror:2 row_mask:0xf bank_mask:0xf bound_ctrl:1
	v_mov_b32_dpp v19, v123 row_ror:1 row_mask:0xf bank_mask:0xf bound_ctrl:1
	v_mov_b32_dpp v139, v123 row_ror:2 row_mask:0xf bank_mask:0xf bound_ctrl:1
	v_mul_f32_e32 v6, v114, v6
	v_add_f32_e32 v114, 1.0, v125
	v_mul_f32_e32 v122, 0xbfb8aa3b, v10
	v_mul_f32_e32 v123, 0xbfb8aa3b, v11
	v_rcp_f32_e32 v114, v114
	v_exp_f32_e32 v122, v122
	v_exp_f32_e32 v123, v123
	v_mov_b32_dpp v136, v178 row_ror:2 row_mask:0xf bank_mask:0xf bound_ctrl:1
	v_mul_f32_e32 v7, v7, v114
	v_add_f32_e32 v114, 1.0, v122
	v_add_f32_e32 v122, 1.0, v123
	v_mov_b32_dpp v137, v179 row_ror:2 row_mask:0xf bank_mask:0xf bound_ctrl:1
	v_rcp_f32_e32 v114, v114
	v_rcp_f32_e32 v122, v122
	v_mov_b32_dpp v134, v178 row_ror:1 row_mask:0xf bank_mask:0xf bound_ctrl:1
	v_mov_b32_dpp v135, v179 row_ror:1 row_mask:0xf bank_mask:0xf bound_ctrl:1
	v_mov_b32_dpp v136, v144 row_shr:2 row_mask:0xf bank_mask:0xf
	v_mov_b32_dpp v137, v145 row_shr:2 row_mask:0xf bank_mask:0xf
	v_mov_b32_dpp v134, v144 row_shr:1 row_mask:0xf bank_mask:0xf
	v_mov_b32_dpp v135, v145 row_shr:1 row_mask:0xf bank_mask:0xf
	v_pk_fma_f32 v[12:13], v[56:57], v[136:137], v[64:65]
	v_mov_b32_dpp v16, v148 row_ror:2 row_mask:0xf bank_mask:0xf bound_ctrl:1
	v_pk_fma_f32 v[12:13], v[40:41], v[134:135], v[12:13]
	v_mov_b32_dpp v17, v149 row_ror:2 row_mask:0xf bank_mask:0xf bound_ctrl:1
	v_pk_fma_f32 v[12:13], v[144:145], v[42:43], v[12:13]
	v_mul_f32_e32 v10, v10, v114
	v_mul_f32_e32 v11, v11, v122
	v_cvt_pk_bf16_f32 v9, v14, v9
	v_mov_b32_dpp v14, v148 row_ror:1 row_mask:0xf bank_mask:0xf bound_ctrl:1
	v_mov_b32_dpp v15, v149 row_ror:1 row_mask:0xf bank_mask:0xf bound_ctrl:1
	v_mul_f32_e32 v10, v12, v10
	v_mul_f32_e32 v11, v13, v11
	v_mov_b32_dpp v16, v120 row_shr:2 row_mask:0xf bank_mask:0xf
	v_mov_b32_dpp v17, v121 row_shr:2 row_mask:0xf bank_mask:0xf
	v_mul_f32_e32 v7, v115, v7
	v_cvt_pk_bf16_f32 v12, v6, v7
	v_cvt_pk_bf16_f32 v13, v10, v11
	v_mov_b32_dpp v14, v120 row_shr:1 row_mask:0xf bank_mask:0xf
	v_mov_b32_dpp v15, v121 row_shr:1 row_mask:0xf bank_mask:0xf
	v_pk_fma_f32 v[10:11], v[50:51], v[16:17], v[62:63]
	v_mov_b32_dpp v138, v76 row_shr:2 row_mask:0xf bank_mask:0xf
	v_pk_fma_f32 v[10:11], v[54:55], v[14:15], v[10:11]
	v_mov_b32_dpp v139, v77 row_shr:2 row_mask:0xf bank_mask:0xf
	v_pk_fma_f32 v[10:11], v[120:121], v[44:45], v[10:11]
	v_mov_b32_dpp v18, v76 row_shr:1 row_mask:0xf bank_mask:0xf
	v_mul_f32_e32 v44, 0xbfb8aa3b, v10
	v_exp_f32_e32 v44, v44
	v_mov_b32_dpp v19, v77 row_shr:1 row_mask:0xf bank_mask:0xf
	v_pk_fma_f32 v[16:17], v[46:47], v[138:139], v[60:61]
	v_mov_b32_dpp v142, v146 row_ror:2 row_mask:0xf bank_mask:0xf bound_ctrl:1
	v_pk_fma_f32 v[16:17], v[38:39], v[18:19], v[16:17]
	v_add_f32_e32 v18, 1.0, v44
	v_mov_b32_dpp v143, v147 row_ror:2 row_mask:0xf bank_mask:0xf bound_ctrl:1
	v_rcp_f32_e32 v18, v18
	v_mul_f32_e32 v19, 0xbfb8aa3b, v11
	v_mov_b32_dpp v140, v146 row_ror:1 row_mask:0xf bank_mask:0xf bound_ctrl:1
; __device__ __forceinline__ unsigned cvt_pk_bf16(float lo, float hi) { unsigned r; asm volatile("v_cvt_pk_bf16_f32 %0, %1, %2" : "=v"(r) : "v"(lo), "v"(hi)); return r; }
; __device__ __forceinline__ float fexp2(float x) { return __builtin_amdgcn_exp2f(x); }
; __device__ __forceinline__ float frcp(float x) { return __builtin_amdgcn_rcpf(x); }
; __device__ __forceinline__ float dpp_shr1(float old, float src) { return __int_as_float(__builtin_amdgcn_update_dpp(__float_as_int(old), __float_as_int(src), 0x111, 0xf, 0xf, false)); }
; __device__ __forceinline__ float dpp_shr2(float old, float src) { return __int_as_float(__builtin_amdgcn_update_dpp(__float_as_int(old), __float_as_int(src), 0x112, 0xf, 0xf, false)); }
; __device__ __forceinline__ float dpp_ror1(float src) { return __int_as_float(__builtin_amdgcn_mov_dpp(__float_as_int(src), 0x121, 0xf, 0xf, true)); }
; __device__ __forceinline__ float dpp_ror2(float src) { return __int_as_float(__builtin_amdgcn_mov_dpp(__float_as_int(src), 0x122, 0xf, 0xf, true)); }
;     __device__ __forceinline__ void operator()(f32x4 (&acc)[2][2][4][2], const Unit& u, int wr, int wc, int fr, int fq) const {
;     ...
;             for (int n = 0; n < 2; ++n) {
;     ...
;                 const f32x4 wg0 = CQ4(0, 0), wg1 = CQ4(0, 1), wg2 = CQ4(0, 2), bg = CQ4(0, 3);
;                 const f32x4 wv0 = CQ4(1, 0), wv1 = CQ4(1, 1), wv2 = CQ4(1, 2), bv = CQ4(1, 3);
;     ...
;                 f32x4 pg1 = {0.f, 0.f, 0.f, 0.f}, pg2 = pg1, pv1 = pg1, pv2 = pg1;
; #pragma unroll
;                 for (int m = 0; m < 4; ++m) {
;                     const f32x4 zg = acc[ai][0][m][n], zv = acc[ai][1][m][n];
;                     f32x4 g1, g2, v1, v2;
; #pragma unroll
;                     for (int j = 0; j < 4; ++j) { g1[j] = dpp_shr1(pg1[j], zg[j]); g2[j] = dpp_shr2(pg2[j], zg[j]); v1[j] = dpp_shr1(pv1[j], zv[j]); v2[j] = dpp_shr2(pv2[j], zv[j]);
;                         pg1[j] = dpp_ror1(zg[j]); pg2[j] = dpp_ror2(zg[j]); pv1[j] = dpp_ror1(zv[j]); pv2[j] = dpp_ror2(zv[j]); }
;                     const f32x4 cg_ = bg + wg0 * g2 + wg1 * g1 + wg2 * zg, cv_ = bv + wv0 * v2 + wv1 * v1 + wv2 * zv;
;                     float o[4];
; #pragma unroll
;                     for (int j = 0; j < 4; ++j) o[j] = cg_[j] * frcp(1.0f + fexp2(-1.4426950409f * cg_[j])) * cv_[j];
;                     pk[m][n][0] = cvt_pk_bf16(o[0], o[1]); pk[m][n][1] = cvt_pk_bf16(o[2], o[3]);
	v_mov_b32_dpp v141, v147 row_ror:1 row_mask:0xf bank_mask:0xf bound_ctrl:1
	v_mov_b32_dpp v142, v82 row_shr:2 row_mask:0xf bank_mask:0xf
	v_mov_b32_dpp v143, v83 row_shr:2 row_mask:0xf bank_mask:0xf
	v_exp_f32_e32 v19, v19
	v_mov_b32_dpp v140, v82 row_shr:1 row_mask:0xf bank_mask:0xf
	v_mov_b32_dpp v141, v83 row_shr:1 row_mask:0xf bank_mask:0xf
	v_pk_fma_f32 v[6:7], v[58:59], v[142:143], v[66:67]
	v_pk_fma_f32 v[16:17], v[76:77], v[36:37], v[16:17]
	v_pk_fma_f32 v[6:7], v[48:49], v[140:141], v[6:7]
	v_mul_f32_e32 v10, v10, v18
	v_pk_fma_f32 v[6:7], v[82:83], v[52:53], v[6:7]
	v_mul_f32_e32 v10, v16, v10
	v_add_f32_e32 v16, 1.0, v19
	v_mul_f32_e32 v18, 0xbfb8aa3b, v6
	v_mul_f32_e32 v19, 0xbfb8aa3b, v7
	v_rcp_f32_e32 v16, v16
	v_exp_f32_e32 v18, v18
	v_exp_f32_e32 v19, v19
	v_mov_b32_dpp v154, v144 row_ror:2 row_mask:0xf bank_mask:0xf bound_ctrl:1
	v_mul_f32_e32 v11, v11, v16
	v_add_f32_e32 v16, 1.0, v18
	v_add_f32_e32 v18, 1.0, v19
	v_mov_b32_dpp v155, v145 row_ror:2 row_mask:0xf bank_mask:0xf bound_ctrl:1
	v_rcp_f32_e32 v16, v16
	v_rcp_f32_e32 v18, v18
	v_mov_b32_dpp v152, v144 row_ror:1 row_mask:0xf bank_mask:0xf bound_ctrl:1
	v_mov_b32_dpp v153, v145 row_ror:1 row_mask:0xf bank_mask:0xf bound_ctrl:1
	v_mov_b32_dpp v154, v78 row_shr:2 row_mask:0xf bank_mask:0xf
	v_mov_b32_dpp v155, v79 row_shr:2 row_mask:0xf bank_mask:0xf
	v_mov_b32_dpp v152, v78 row_shr:1 row_mask:0xf bank_mask:0xf
	v_mov_b32_dpp v153, v79 row_shr:1 row_mask:0xf bank_mask:0xf
	v_pk_fma_f32 v[14:15], v[56:57], v[154:155], v[64:65]
	v_mul_f32_e32 v11, v17, v11
	v_pk_fma_f32 v[14:15], v[40:41], v[152:153], v[14:15]
	v_mul_f32_e32 v6, v6, v16
	v_pk_fma_f32 v[14:15], v[78:79], v[42:43], v[14:15]
	v_mul_f32_e32 v7, v7, v18
	s_setprio 1
	v_mul_f32_e32 v6, v14, v6
	v_mul_f32_e32 v7, v15, v7
	v_cvt_pk_bf16_f32 v16, v10, v11
	v_mov_b32_e32 v10, v2
	v_mov_b32_e32 v11, v2
	v_cvt_pk_bf16_f32 v17, v6, v7
	v_mov_b32_e32 v6, v2
	v_mov_b32_dpp v10, v130 row_shr:2 row_mask:0xf bank_mask:0xf
	v_mov_b32_e32 v7, v2
	v_mov_b32_dpp v11, v131 row_shr:2 row_mask:0xf bank_mask:0xf
	v_mov_b32_dpp v6, v130 row_shr:1 row_mask:0xf bank_mask:0xf
	v_mov_b32_dpp v7, v131 row_shr:1 row_mask:0xf bank_mask:0xf
	v_mov_b32_e32 v46, v2
	v_mov_b32_e32 v47, v2
	v_pk_fma_f32 v[10:11], v[100:101], v[10:11], v[150:151]
	v_mov_b32_e32 v44, v2
	v_mov_b32_dpp v46, v128 row_shr:2 row_mask:0xf bank_mask:0xf
	v_mov_b32_e32 v45, v2
	v_mov_b32_dpp v47, v129 row_shr:2 row_mask:0xf bank_mask:0xf
	v_pk_fma_f32 v[6:7], v[108:109], v[6:7], v[10:11]
	v_mov_b32_dpp v44, v128 row_shr:1 row_mask:0xf bank_mask:0xf
	v_mov_b32_dpp v45, v129 row_shr:1 row_mask:0xf bank_mask:0xf
	v_pk_fma_f32 v[46:47], v[112:113], v[46:47], v[160:161]
	v_pk_fma_f32 v[6:7], v[130:131], v[92:93], v[6:7]
	v_pk_fma_f32 v[10:11], v[96:97], v[44:45], v[46:47]
	v_mul_f32_e32 v46, 0xbfb8aa3b, v6
	v_exp_f32_e32 v46, v46
	v_mov_b32_e32 v18, v2
	v_mov_b32_e32 v19, v2
	v_mov_b32_e32 v50, v2
	v_mov_b32_e32 v51, v2
	v_mov_b32_e32 v14, v2
	v_mov_b32_dpp v18, v116 row_shr:2 row_mask:0xf bank_mask:0xf
	v_mov_b32_e32 v15, v2
	v_mov_b32_dpp v19, v117 row_shr:2 row_mask:0xf bank_mask:0xf
	v_mov_b32_e32 v48, v2
	v_mov_b32_dpp v50, v118 row_shr:2 row_mask:0xf bank_mask:0xf
	v_mov_b32_e32 v49, v2
	v_mov_b32_dpp v51, v119 row_shr:2 row_mask:0xf bank_mask:0xf
	v_mov_b32_dpp v14, v116 row_shr:1 row_mask:0xf bank_mask:0xf
	v_mov_b32_dpp v15, v117 row_shr:1 row_mask:0xf bank_mask:0xf
	v_mov_b32_dpp v48, v118 row_shr:1 row_mask:0xf bank_mask:0xf
	v_mov_b32_dpp v49, v119 row_shr:1 row_mask:0xf bank_mask:0xf
	v_pk_fma_f32 v[44:45], v[98:99], v[50:51], v[106:107]
	v_pk_fma_f32 v[18:19], v[94:95], v[18:19], v[102:103]
	v_pk_fma_f32 v[10:11], v[128:129], v[104:105], v[10:11]
	v_pk_fma_f32 v[14:15], v[86:87], v[14:15], v[18:19]
	v_pk_fma_f32 v[18:19], v[88:89], v[48:49], v[44:45]
	v_add_f32_e32 v44, 1.0, v46
	v_rcp_f32_e32 v44, v44
	v_mul_f32_e32 v45, 0xbfb8aa3b, v7
	v_exp_f32_e32 v45, v45
	v_pk_fma_f32 v[14:15], v[116:117], v[84:85], v[14:15]
	v_mul_f32_e32 v6, v6, v44
	v_mul_f32_e32 v6, v14, v6
	v_add_f32_e32 v14, 1.0, v45
	v_mul_f32_e32 v44, 0xbfb8aa3b, v10
	v_mul_f32_e32 v45, 0xbfb8aa3b, v11
	v_rcp_f32_e32 v14, v14
	v_exp_f32_e32 v44, v44
	v_exp_f32_e32 v45, v45
	v_mov_b32_dpp v38, v130 row_ror:2 row_mask:0xf bank_mask:0xf bound_ctrl:1
	v_mul_f32_e32 v7, v7, v14
	v_add_f32_e32 v14, 1.0, v44
	v_add_f32_e32 v44, 1.0, v45
	v_rcp_f32_e32 v14, v14
	v_rcp_f32_e32 v44, v44
	v_mov_b32_dpp v39, v131 row_ror:2 row_mask:0xf bank_mask:0xf bound_ctrl:1
	v_mov_b32_dpp v54, v128 row_ror:2 row_mask:0xf bank_mask:0xf bound_ctrl:1
	v_mov_b32_dpp v55, v129 row_ror:2 row_mask:0xf bank_mask:0xf bound_ctrl:1
	v_pk_fma_f32 v[18:19], v[118:119], v[90:91], v[18:19]
	v_mul_f32_e32 v10, v10, v14
	v_mul_f32_e32 v11, v11, v44
	v_mov_b32_dpp v36, v130 row_ror:1 row_mask:0xf bank_mask:0xf bound_ctrl:1
	v_mov_b32_dpp v37, v131 row_ror:1 row_mask:0xf bank_mask:0xf bound_ctrl:1
	v_mov_b32_dpp v52, v128 row_ror:1 row_mask:0xf bank_mask:0xf bound_ctrl:1
	v_mov_b32_dpp v53, v129 row_ror:1 row_mask:0xf bank_mask:0xf bound_ctrl:1
	v_mul_f32_e32 v7, v15, v7
	v_mul_f32_e32 v10, v18, v10
	v_mul_f32_e32 v11, v19, v11
	v_mov_b32_dpp v38, v34 row_shr:2 row_mask:0xf bank_mask:0xf
	v_mov_b32_dpp v39, v35 row_shr:2 row_mask:0xf bank_mask:0xf
	v_mov_b32_dpp v54, v32 row_shr:2 row_mask:0xf bank_mask:0xf
	v_mov_b32_dpp v55, v33 row_shr:2 row_mask:0xf bank_mask:0xf
	v_cvt_pk_bf16_f32 v6, v6, v7
	v_cvt_pk_bf16_f32 v7, v10, v11
	v_mov_b32_dpp v36, v34 row_shr:1 row_mask:0xf bank_mask:0xf
	v_mov_b32_dpp v37, v35 row_shr:1 row_mask:0xf bank_mask:0xf
	v_mov_b32_dpp v52, v32 row_shr:1 row_mask:0xf bank_mask:0xf
; __device__ __forceinline__ unsigned cvt_pk_bf16(float lo, float hi) { unsigned r; asm volatile("v_cvt_pk_bf16_f32 %0, %1, %2" : "=v"(r) : "v"(lo), "v"(hi)); return r; }
; __device__ __forceinline__ float fexp2(float x) { return __builtin_amdgcn_exp2f(x); }
; __device__ __forceinline__ float frcp(float x) { return __builtin_amdgcn_rcpf(x); }
; __device__ __forceinline__ float dpp_shr1(float old, float src) { return __int_as_float(__builtin_amdgcn_update_dpp(__float_as_int(old), __float_as_int(src), 0x111, 0xf, 0xf, false)); }
; __device__ __forceinline__ float dpp_shr2(float old, float src) { return __int_as_float(__builtin_amdgcn_update_dpp(__float_as_int(old), __float_as_int(src), 0x112, 0xf, 0xf, false)); }
; __device__ __forceinline__ float dpp_ror1(float src) { return __int_as_float(__builtin_amdgcn_mov_dpp(__float_as_int(src), 0x121, 0xf, 0xf, true)); }
; __device__ __forceinline__ float dpp_ror2(float src) { return __int_as_float(__builtin_amdgcn_mov_dpp(__float_as_int(src), 0x122, 0xf, 0xf, true)); }
;     __device__ __forceinline__ void operator()(f32x4 (&acc)[2][2][4][2], const Unit& u, int wr, int wc, int fr, int fq) const {
;     ...
;                 for (int m = 0; m < 4; ++m) {
;                     const f32x4 zg = acc[ai][0][m][n], zv = acc[ai][1][m][n];
;                     f32x4 g1, g2, v1, v2;
; #pragma unroll
;                     for (int j = 0; j < 4; ++j) { g1[j] = dpp_shr1(pg1[j], zg[j]); g2[j] = dpp_shr2(pg2[j], zg[j]); v1[j] = dpp_shr1(pv1[j], zv[j]); v2[j] = dpp_shr2(pv2[j], zv[j]);
;                         pg1[j] = dpp_ror1(zg[j]); pg2[j] = dpp_ror2(zg[j]); pv1[j] = dpp_ror1(zv[j]); pv2[j] = dpp_ror2(zv[j]); }
;                     const f32x4 cg_ = bg + wg0 * g2 + wg1 * g1 + wg2 * zg, cv_ = bv + wv0 * v2 + wv1 * v1 + wv2 * zv;
;                     float o[4];
; #pragma unroll
;                     for (int j = 0; j < 4; ++j) o[j] = cg_[j] * frcp(1.0f + fexp2(-1.4426950409f * cg_[j])) * cv_[j];
;                     pk[m][n][0] = cvt_pk_bf16(o[0], o[1]); pk[m][n][1] = cvt_pk_bf16(o[2], o[3]);
	v_mov_b32_dpp v53, v33 row_shr:1 row_mask:0xf bank_mask:0xf
	v_pk_fma_f32 v[10:11], v[112:113], v[54:55], v[160:161]
	v_pk_fma_f32 v[38:39], v[100:101], v[38:39], v[150:151]
	v_pk_fma_f32 v[10:11], v[96:97], v[52:53], v[10:11]
	v_pk_fma_f32 v[36:37], v[108:109], v[36:37], v[38:39]
	v_mov_b32_dpp v48, v32 row_ror:1 row_mask:0xf bank_mask:0xf bound_ctrl:1
	v_mov_b32_dpp v50, v32 row_ror:2 row_mask:0xf bank_mask:0xf bound_ctrl:1
	v_mov_b32_dpp v49, v33 row_ror:1 row_mask:0xf bank_mask:0xf bound_ctrl:1
	v_mov_b32_dpp v51, v33 row_ror:2 row_mask:0xf bank_mask:0xf bound_ctrl:1
	v_pk_fma_f32 v[10:11], v[32:33], v[104:105], v[10:11]
	v_pk_fma_f32 v[32:33], v[34:35], v[92:93], v[36:37]
	v_mov_b32_dpp v58, v118 row_ror:2 row_mask:0xf bank_mask:0xf bound_ctrl:1
	v_mul_f32_e32 v38, 0xbfb8aa3b, v32
	v_mov_b32_dpp v59, v119 row_ror:2 row_mask:0xf bank_mask:0xf bound_ctrl:1
	v_exp_f32_e32 v38, v38
	v_mov_b32_dpp v56, v118 row_ror:1 row_mask:0xf bank_mask:0xf bound_ctrl:1
	v_mov_b32_dpp v57, v119 row_ror:1 row_mask:0xf bank_mask:0xf bound_ctrl:1
	v_mov_b32_dpp v58, v30 row_shr:2 row_mask:0xf bank_mask:0xf
	v_mov_b32_dpp v59, v31 row_shr:2 row_mask:0xf bank_mask:0xf
	v_mov_b32_dpp v14, v34 row_ror:1 row_mask:0xf bank_mask:0xf bound_ctrl:1
	v_mov_b32_dpp v18, v34 row_ror:2 row_mask:0xf bank_mask:0xf bound_ctrl:1
	v_mov_b32_dpp v15, v35 row_ror:1 row_mask:0xf bank_mask:0xf bound_ctrl:1
	v_mov_b32_dpp v19, v35 row_ror:2 row_mask:0xf bank_mask:0xf bound_ctrl:1
	v_mov_b32_dpp v56, v30 row_shr:1 row_mask:0xf bank_mask:0xf
	v_mov_b32_dpp v57, v31 row_shr:1 row_mask:0xf bank_mask:0xf
	v_pk_fma_f32 v[34:35], v[98:99], v[58:59], v[106:107]
	v_mov_b32_dpp v60, v30 row_ror:1 row_mask:0xf bank_mask:0xf bound_ctrl:1
	v_pk_fma_f32 v[34:35], v[88:89], v[56:57], v[34:35]
	v_mov_b32_dpp v62, v30 row_ror:2 row_mask:0xf bank_mask:0xf bound_ctrl:1
	v_mov_b32_dpp v61, v31 row_ror:1 row_mask:0xf bank_mask:0xf bound_ctrl:1
	v_mov_b32_dpp v63, v31 row_ror:2 row_mask:0xf bank_mask:0xf bound_ctrl:1
	v_pk_fma_f32 v[30:31], v[30:31], v[90:91], v[34:35]
	v_add_f32_e32 v34, 1.0, v38
	v_mov_b32_dpp v42, v116 row_ror:2 row_mask:0xf bank_mask:0xf bound_ctrl:1
	v_mov_b32_dpp v43, v117 row_ror:2 row_mask:0xf bank_mask:0xf bound_ctrl:1
	v_rcp_f32_e32 v34, v34
	v_mul_f32_e32 v35, 0xbfb8aa3b, v33
	v_mov_b32_dpp v40, v116 row_ror:1 row_mask:0xf bank_mask:0xf bound_ctrl:1
	v_mov_b32_dpp v41, v117 row_ror:1 row_mask:0xf bank_mask:0xf bound_ctrl:1
	v_mov_b32_dpp v42, v28 row_shr:2 row_mask:0xf bank_mask:0xf
	v_mov_b32_dpp v43, v29 row_shr:2 row_mask:0xf bank_mask:0xf
	v_exp_f32_e32 v35, v35
	v_mov_b32_dpp v40, v28 row_shr:1 row_mask:0xf bank_mask:0xf
	v_mov_b32_dpp v41, v29 row_shr:1 row_mask:0xf bank_mask:0xf
	v_pk_fma_f32 v[36:37], v[94:95], v[42:43], v[102:103]
	v_mov_b32_dpp v44, v28 row_ror:1 row_mask:0xf bank_mask:0xf bound_ctrl:1
	v_pk_fma_f32 v[36:37], v[86:87], v[40:41], v[36:37]
	v_mov_b32_dpp v46, v28 row_ror:2 row_mask:0xf bank_mask:0xf bound_ctrl:1
	v_mov_b32_dpp v45, v29 row_ror:1 row_mask:0xf bank_mask:0xf bound_ctrl:1
	v_mov_b32_dpp v47, v29 row_ror:2 row_mask:0xf bank_mask:0xf bound_ctrl:1
	v_pk_fma_f32 v[28:29], v[28:29], v[84:85], v[36:37]
	v_mul_f32_e32 v32, v32, v34
	v_mul_f32_e32 v28, v28, v32
	v_add_f32_e32 v32, 1.0, v35
	v_mul_f32_e32 v34, 0xbfb8aa3b, v10
	v_rcp_f32_e32 v32, v32
	v_exp_f32_e32 v34, v34
	v_mul_f32_e32 v35, 0xbfb8aa3b, v11
	v_exp_f32_e32 v35, v35
	v_mul_f32_e32 v32, v33, v32
	v_add_f32_e32 v33, 1.0, v34
	v_rcp_f32_e32 v33, v33
	v_add_f32_e32 v34, 1.0, v35
	v_rcp_f32_e32 v34, v34
	v_mov_b32_dpp v18, v26 row_shr:2 row_mask:0xf bank_mask:0xf
	v_mov_b32_dpp v19, v27 row_shr:2 row_mask:0xf bank_mask:0xf
	v_mul_f32_e32 v10, v10, v33
	v_mov_b32_dpp v14, v26 row_shr:1 row_mask:0xf bank_mask:0xf
	v_mov_b32_dpp v15, v27 row_shr:1 row_mask:0xf bank_mask:0xf
	v_pk_fma_f32 v[18:19], v[100:101], v[18:19], v[150:151]
	v_mul_f32_e32 v30, v30, v10
	v_mul_f32_e32 v10, v11, v34
	v_pk_fma_f32 v[14:15], v[108:109], v[14:15], v[18:19]
	v_mul_f32_e32 v29, v29, v32
	v_mul_f32_e32 v11, v31, v10
	v_mov_b32_dpp v46, v20 row_shr:2 row_mask:0xf bank_mask:0xf
	v_mov_b32_dpp v47, v21 row_shr:2 row_mask:0xf bank_mask:0xf
	v_pk_fma_f32 v[14:15], v[26:27], v[92:93], v[14:15]
	v_cvt_pk_bf16_f32 v10, v28, v29
	v_cvt_pk_bf16_f32 v11, v30, v11
	v_mov_b32_dpp v28, v26 row_ror:1 row_mask:0xf bank_mask:0xf bound_ctrl:1
	v_mov_b32_dpp v30, v26 row_ror:2 row_mask:0xf bank_mask:0xf bound_ctrl:1
	v_mov_b32_dpp v29, v27 row_ror:1 row_mask:0xf bank_mask:0xf bound_ctrl:1
	v_mov_b32_dpp v31, v27 row_ror:2 row_mask:0xf bank_mask:0xf bound_ctrl:1
	v_mov_b32_dpp v50, v24 row_shr:2 row_mask:0xf bank_mask:0xf
	v_mov_b32_dpp v51, v25 row_shr:2 row_mask:0xf bank_mask:0xf
	v_pk_fma_f32 v[26:27], v[94:95], v[46:47], v[102:103]
	v_mul_f32_e32 v46, 0xbfb8aa3b, v14
	v_mov_b32_dpp v48, v24 row_shr:1 row_mask:0xf bank_mask:0xf
	v_mov_b32_dpp v49, v25 row_shr:1 row_mask:0xf bank_mask:0xf
	v_pk_fma_f32 v[50:51], v[112:113], v[50:51], v[160:161]
	v_exp_f32_e32 v46, v46
	v_mov_b32_dpp v62, v22 row_shr:2 row_mask:0xf bank_mask:0xf
	v_mov_b32_dpp v63, v23 row_shr:2 row_mask:0xf bank_mask:0xf
	v_pk_fma_f32 v[18:19], v[96:97], v[48:49], v[50:51]
	v_mov_b32_dpp v60, v22 row_shr:1 row_mask:0xf bank_mask:0xf
	v_mov_b32_dpp v36, v24 row_ror:1 row_mask:0xf bank_mask:0xf bound_ctrl:1
; __device__ __forceinline__ unsigned cvt_pk_bf16(float lo, float hi) { unsigned r; asm volatile("v_cvt_pk_bf16_f32 %0, %1, %2" : "=v"(r) : "v"(lo), "v"(hi)); return r; }
; __device__ __forceinline__ float fexp2(float x) { return __builtin_amdgcn_exp2f(x); }
; __device__ __forceinline__ float frcp(float x) { return __builtin_amdgcn_rcpf(x); }
; __device__ __forceinline__ float dpp_shr1(float old, float src) { return __int_as_float(__builtin_amdgcn_update_dpp(__float_as_int(old), __float_as_int(src), 0x111, 0xf, 0xf, false)); }
; __device__ __forceinline__ float dpp_shr2(float old, float src) { return __int_as_float(__builtin_amdgcn_update_dpp(__float_as_int(old), __float_as_int(src), 0x112, 0xf, 0xf, false)); }
; __device__ __forceinline__ float dpp_ror1(float src) { return __int_as_float(__builtin_amdgcn_mov_dpp(__float_as_int(src), 0x121, 0xf, 0xf, true)); }
; __device__ __forceinline__ float dpp_ror2(float src) { return __int_as_float(__builtin_amdgcn_mov_dpp(__float_as_int(src), 0x122, 0xf, 0xf, true)); }
;     __device__ __forceinline__ void operator()(f32x4 (&acc)[2][2][4][2], const Unit& u, int wr, int wc, int fr, int fq) const {
;     ...
;                 for (int m = 0; m < 4; ++m) {
;                     const f32x4 zg = acc[ai][0][m][n], zv = acc[ai][1][m][n];
;                     f32x4 g1, g2, v1, v2;
; #pragma unroll
;                     for (int j = 0; j < 4; ++j) { g1[j] = dpp_shr1(pg1[j], zg[j]); g2[j] = dpp_shr2(pg2[j], zg[j]); v1[j] = dpp_shr1(pv1[j], zv[j]); v2[j] = dpp_shr2(pv2[j], zv[j]);
;                         pg1[j] = dpp_ror1(zg[j]); pg2[j] = dpp_ror2(zg[j]); pv1[j] = dpp_ror1(zv[j]); pv2[j] = dpp_ror2(zv[j]); }
;                     const f32x4 cg_ = bg + wg0 * g2 + wg1 * g1 + wg2 * zg, cv_ = bv + wv0 * v2 + wv1 * v1 + wv2 * zv;
;                     float o[4];
; #pragma unroll
;                     for (int j = 0; j < 4; ++j) o[j] = cg_[j] * frcp(1.0f + fexp2(-1.4426950409f * cg_[j])) * cv_[j];
;                     pk[m][n][0] = cvt_pk_bf16(o[0], o[1]); pk[m][n][1] = cvt_pk_bf16(o[2], o[3]);
;                 }
;             }
; #pragma unroll
;             for (int m = 0; m < 4; ++m) { u32x4 w; w.x = pk[m][0][0]; w.y = pk[m][0][1]; w.z = pk[m][1][0]; w.w = pk[m][1][1];
;                 *(u32x4*)(act + (size_t)(row0 + ai * HALF + m * 16) * 2816 + f0) = w; }
;             asm volatile("" ::: "memory");
;         }
	v_mov_b32_dpp v38, v24 row_ror:2 row_mask:0xf bank_mask:0xf bound_ctrl:1
	v_mov_b32_dpp v61, v23 row_shr:1 row_mask:0xf bank_mask:0xf
	v_mov_b32_dpp v37, v25 row_ror:1 row_mask:0xf bank_mask:0xf bound_ctrl:1
	v_mov_b32_dpp v39, v25 row_ror:2 row_mask:0xf bank_mask:0xf bound_ctrl:1
	v_pk_fma_f32 v[18:19], v[24:25], v[104:105], v[18:19]
	v_pk_fma_f32 v[24:25], v[98:99], v[62:63], v[106:107]
	v_mov_b32_dpp v40, v22 row_ror:1 row_mask:0xf bank_mask:0xf bound_ctrl:1
	v_pk_fma_f32 v[24:25], v[88:89], v[60:61], v[24:25]
	v_mov_b32_dpp v42, v22 row_ror:2 row_mask:0xf bank_mask:0xf bound_ctrl:1
	v_mov_b32_dpp v41, v23 row_ror:1 row_mask:0xf bank_mask:0xf bound_ctrl:1
	v_mov_b32_dpp v43, v23 row_ror:2 row_mask:0xf bank_mask:0xf bound_ctrl:1
	v_pk_fma_f32 v[22:23], v[22:23], v[90:91], v[24:25]
	v_add_f32_e32 v24, 1.0, v46
	v_rcp_f32_e32 v24, v24
	v_mul_f32_e32 v25, 0xbfb8aa3b, v15
	v_exp_f32_e32 v25, v25
	v_mov_b32_dpp v44, v20 row_shr:1 row_mask:0xf bank_mask:0xf
	v_mov_b32_dpp v45, v21 row_shr:1 row_mask:0xf bank_mask:0xf
	v_pk_fma_f32 v[26:27], v[86:87], v[44:45], v[26:27]
	v_mov_b32_dpp v32, v20 row_ror:1 row_mask:0xf bank_mask:0xf bound_ctrl:1
	v_mov_b32_dpp v34, v20 row_ror:2 row_mask:0xf bank_mask:0xf bound_ctrl:1
	v_mov_b32_dpp v33, v21 row_ror:1 row_mask:0xf bank_mask:0xf bound_ctrl:1
	v_mov_b32_dpp v35, v21 row_ror:2 row_mask:0xf bank_mask:0xf bound_ctrl:1
	v_pk_fma_f32 v[20:21], v[20:21], v[84:85], v[26:27]
	v_mul_f32_e32 v14, v14, v24
	v_mul_f32_e32 v14, v20, v14
	v_add_f32_e32 v20, 1.0, v25
	v_mul_f32_e32 v24, 0xbfb8aa3b, v18
	v_rcp_f32_e32 v20, v20
	v_exp_f32_e32 v24, v24
	v_mul_f32_e32 v25, 0xbfb8aa3b, v19
	v_mov_b32_dpp v30, v80 row_shr:2 row_mask:0xf bank_mask:0xf
	v_mul_f32_e32 v15, v15, v20
	v_add_f32_e32 v20, 1.0, v24
	v_rcp_f32_e32 v20, v20
	v_mov_b32_dpp v31, v81 row_shr:2 row_mask:0xf bank_mask:0xf
	v_exp_f32_e32 v25, v25
	v_mul_f32_e32 v15, v21, v15
	v_mul_f32_e32 v18, v18, v20
	v_mov_b32_dpp v28, v80 row_shr:1 row_mask:0xf bank_mask:0xf
	v_mov_b32_dpp v29, v81 row_shr:1 row_mask:0xf bank_mask:0xf
	v_pk_fma_f32 v[20:21], v[100:101], v[30:31], v[150:151]
	v_add_f32_e32 v24, 1.0, v25
	v_pk_fma_f32 v[20:21], v[108:109], v[28:29], v[20:21]
	v_rcp_f32_e32 v24, v24
	v_pk_fma_f32 v[20:21], v[80:81], v[92:93], v[20:21]
	v_mul_f32_e32 v18, v22, v18
	v_mul_f32_e32 v26, 0xbfb8aa3b, v20
	v_exp_f32_e32 v26, v26
	v_mul_f32_e32 v19, v19, v24
	v_mul_f32_e32 v27, 0xbfb8aa3b, v21
	v_mul_f32_e32 v19, v23, v19
	v_add_f32_e32 v26, 1.0, v26
	v_rcp_f32_e32 v26, v26
	v_mov_b32_dpp v34, v70 row_shr:2 row_mask:0xf bank_mask:0xf
	v_mov_b32_dpp v35, v71 row_shr:2 row_mask:0xf bank_mask:0xf
	v_mov_b32_dpp v38, v74 row_shr:2 row_mask:0xf bank_mask:0xf
	v_mov_b32_dpp v39, v75 row_shr:2 row_mask:0xf bank_mask:0xf
	v_exp_f32_e32 v27, v27
	v_cvt_pk_bf16_f32 v14, v14, v15
	v_cvt_pk_bf16_f32 v15, v18, v19
	v_mov_b32_dpp v32, v70 row_shr:1 row_mask:0xf bank_mask:0xf
	v_mov_b32_dpp v33, v71 row_shr:1 row_mask:0xf bank_mask:0xf
	v_mov_b32_dpp v36, v74 row_shr:1 row_mask:0xf bank_mask:0xf
	v_mov_b32_dpp v37, v75 row_shr:1 row_mask:0xf bank_mask:0xf
	v_pk_fma_f32 v[18:19], v[112:113], v[38:39], v[160:161]
	v_pk_fma_f32 v[24:25], v[94:95], v[34:35], v[102:103]
	v_pk_fma_f32 v[18:19], v[96:97], v[36:37], v[18:19]
	v_pk_fma_f32 v[24:25], v[86:87], v[32:33], v[24:25]
	v_pk_fma_f32 v[18:19], v[74:75], v[104:105], v[18:19]
	v_pk_fma_f32 v[24:25], v[70:71], v[84:85], v[24:25]
	v_mul_f32_e32 v20, v20, v26
	v_mul_f32_e32 v20, v24, v20
	v_add_f32_e32 v24, 1.0, v27
	v_mul_f32_e32 v26, 0xbfb8aa3b, v18
	v_rcp_f32_e32 v24, v24
	v_exp_f32_e32 v26, v26
	v_mul_f32_e32 v27, 0xbfb8aa3b, v19
	v_exp_f32_e32 v27, v27
	v_mul_f32_e32 v21, v21, v24
	v_add_f32_e32 v24, 1.0, v26
	v_rcp_f32_e32 v24, v24
	v_add_f32_e32 v26, 1.0, v27
	v_mov_b32_dpp v42, v72 row_shr:2 row_mask:0xf bank_mask:0xf
	v_mov_b32_dpp v43, v73 row_shr:2 row_mask:0xf bank_mask:0xf
	v_rcp_f32_e32 v26, v26
	v_mov_b32_dpp v40, v72 row_shr:1 row_mask:0xf bank_mask:0xf
	v_mov_b32_dpp v41, v73 row_shr:1 row_mask:0xf bank_mask:0xf
	v_pk_fma_f32 v[22:23], v[98:99], v[42:43], v[106:107]
	v_mul_f32_e32 v18, v18, v24
	v_pk_fma_f32 v[22:23], v[88:89], v[40:41], v[22:23]
	v_mul_f32_e32 v21, v25, v21
	v_pk_fma_f32 v[22:23], v[72:73], v[90:91], v[22:23]
	v_add_u32_e32 v177, 0x90, v176
	v_mul_f32_e32 v22, v22, v18
	v_mul_f32_e32 v18, v19, v26
	v_mul_f32_e32 v19, v23, v18
	s_setprio 0
	v_cvt_pk_bf16_f32 v18, v20, v21
	v_mad_i64_i32 v[20:21], s[18:19], v246, s22, v[110:111]
	v_lshl_add_u64 v[20:21], v[20:21], 0, v[68:69]
	v_cvt_pk_bf16_f32 v19, v22, v19
	global_store_dwordx4 v[20:21], v[4:7], off
	v_add_u32_e32 v247, 0xa0, v176
	v_add_u32_e32 v248, 0xb0, v176
	v_mad_i64_i32 v[4:5], s[18:19], v177, s22, v[110:111]
	v_lshl_add_u64 v[4:5], v[4:5], 0, v[68:69]
	global_store_dwordx4 v[4:5], v[8:11], off
	v_mad_i64_i32 v[4:5], s[18:19], v247, s22, v[110:111]
	v_lshl_add_u64 v[4:5], v[4:5], 0, v[68:69]
	global_store_dwordx4 v[4:5], v[12:15], off
	v_mad_i64_i32 v[4:5], s[18:19], v248, s22, v[110:111]
	v_lshl_add_u64 v[4:5], v[4:5], 0, v[68:69]
	global_store_dwordx4 v[4:5], v[16:19], off
	v_readlane_b32 s46, v254, 53
	s_andn2_b64 vcc, exec, s[42:43]
	s_mov_b64 s[18:19], -1
	v_readlane_b32 s47, v254, 54
	s_cbranch_vccnz .LBB0_31
	v_readlane_b32 s18, v252, 2
	v_readlane_b32 s19, v252, 3
	s_andn2_b64 vcc, exec, s[18:19]
	s_cbranch_vccnz .LBB0_30
	s_barrier
	s_branch .LBB0_30
